# K loops: last LDS-DMA issues of each load segment moved into the wave's own MFMA burst, vmcnt recounted; saddr DMA; aligned loops; hand-written scan
# speedup vs baseline: 1.0032x; 1.0032x over previous
; #define PG8_STAGE(bufoff, gbase, voff) do { _Pragma("unroll") for (int _i = 0; _i < 2; ++_i) \
;         __builtin_amdgcn_global_load_lds((const unsigned*)((const char*)(gbase) + (voff)[_i]), (PG8_LAS unsigned*)(lds + (bufoff) + ldsw + _i * 8192), 16, 0, 0); } while (0)
; #define PG8_LDA(dst, b, h) do { _Pragma("unroll") for (int m = 0; m < 4; ++m) _Pragma("unroll") for (int k = 0; k < 2; ++k) dst[m][k] = *(const PG8_LAS bf16x8*)(lds + PG8_SA(b, h) + aoff + m * 2048 + k * 1024); } while (0)
; #define PG8_LDB(dst, b, h) do { _Pragma("unroll") for (int n = 0; n < 2; ++n) _Pragma("unroll") for (int k = 0; k < 2; ++k) dst[n][k] = *(const PG8_LAS bf16x8*)(lds + PG8_SB(b, h) + boff + n * 2048 + k * 1024); } while (0)
; #define PG8_MMA(ai, bj, At, Bt) do { __builtin_amdgcn_s_setprio(1); _Pragma("unroll") for (int m = 0; m < 4; ++m) _Pragma("unroll") for (int n = 0; n < 2; ++n) _Pragma("unroll") for (int k = 0; k < 2; ++k) \
;         acc[ai][bj][m][n] = __builtin_amdgcn_mfma_f32_16x16x32_bf16(Bt[n][k], At[m][k], acc[ai][bj][m][n], 0, 0, 0); __builtin_amdgcn_s_setprio(0); } while (0)
; #define PG8_WAIT_V(n) asm volatile("s_waitcnt vmcnt(" #n ")" ::: "memory")
; #define PG8_WAIT_L(n) asm volatile("s_waitcnt lgkmcnt(" #n ")" ::: "memory")
; template <class Epi, class Sched, bool ALIGN_EPI = false, bool SP2 = false>
; __device__ __forceinline__ void gemm_phase(PG8_LAS unsigned char* lds, const Gemm g, const Sched& S, const Epi& E) {
;     ...
;             const bool last = (t == nt - 2);
;             const char* a1 = cA + (size_t)(t + 1) * kstep;
;             const char* a2 = last ? nA : cA + (size_t)(t + 2) * kstep; const char* b2 = last ? nB : cB + (size_t)(t + 2) * kstep;
;             const char* a3 = a2 + kstep; const char* b3 = b2 + kstep;
;             if (last && has_next) S.a_ready(nxt);
;             if constexpr (SP2) {
;             PG8_LDB(B0, 0, 0); PG8_LDB(B1, 0, 1); PG8_SCHED; PG8_LDA(At, 0, 0); PG8_STAGE(PG8_SA(1, 1), a1 + hstep, voffA);
;             PG8_WAIT_V(8); PG8_WAIT_L(0); PG8_BAR; PG8_MMA(0, 0, At, B0); PG8_MMA(0, 1, At, B1); PG8_BAR; PG8_SCHED;
;             PG8_LDA(At, 0, 1); PG8_STAGE(PG8_SB(0, 0), b2, voffB); PG8_STAGE(PG8_SB(0, 1), b2 + hstep, voffB); PG8_STAGE(PG8_SA(0, 0), a2, voffA);
;             PG8_WAIT_V(8); PG8_WAIT_L(0); PG8_BAR; PG8_MMA(1, 0, At, B0); PG8_MMA(1, 1, At, B1); PG8_BAR; PG8_SCHED;
.LBB0_301:
	s_add_u32 s38, s36, 0xfff80080
	s_addc_u32 s39, s37, -1
	s_add_i32 s61, 0, 0x10000
	s_cmp_eq_u32 s60, 28
	s_cselect_b32 s41, s11, s39
	s_cselect_b32 s40, s13, s38
	s_cselect_b32 s39, s56, s59
	s_cselect_b32 s38, s57, s58
	s_add_i32 s64, 0, 0x14000
	v_add_u32_e32 v158, s61, v150
	v_add_u32_e32 v162, s64, v150
	ds_read_b128 v[142:145], v158
	ds_read_b128 v[146:149], v158 offset:1024
	ds_read_b128 v[154:157], v158 offset:2048
	ds_read_b128 v[158:161], v158 offset:3072
	ds_read_b128 v[174:177], v162
	ds_read_b128 v[178:181], v162 offset:1024
	ds_read_b128 v[204:207], v162 offset:2048
	ds_read_b128 v[208:211], v162 offset:3072
	s_add_i32 m0, s47, 0xc000
	ds_read_b128 v[212:215], v153
	ds_read_b128 v[216:219], v153 offset:1024
	ds_read_b128 v[220:223], v153 offset:2048
	ds_read_b128 v[224:227], v153 offset:3072
	ds_read_b128 v[228:231], v153 offset:4096
	ds_read_b128 v[232:235], v153 offset:5120
	ds_read_b128 v[236:239], v153 offset:6144
	ds_read_b128 v[240:243], v153 offset:7168
	global_load_lds_dwordx4 v138, s[36:37]
	s_nop 0
	s_waitcnt vmcnt(7)
	s_waitcnt lgkmcnt(0)
	s_barrier
	s_setprio 1
	s_waitcnt lgkmcnt(0)
	v_mfma_f32_16x16x32_bf16 v[128:131], v[142:145], v[212:215], v[128:131]
	v_mfma_f32_16x16x32_bf16 v[120:123], v[154:157], v[212:215], v[120:123]
	v_mfma_f32_16x16x32_bf16 v[112:115], v[142:145], v[220:223], v[112:115]
	s_add_i32 m0, s47, 0xe000
	v_mfma_f32_16x16x32_bf16 v[104:107], v[154:157], v[220:223], v[104:107]
	global_load_lds_dwordx4 v140, s[36:37]
	v_mfma_f32_16x16x32_bf16 v[96:99], v[142:145], v[228:231], v[96:99]
	v_mfma_f32_16x16x32_bf16 v[88:91], v[154:157], v[228:231], v[88:91]
	v_mfma_f32_16x16x32_bf16 v[80:83], v[142:145], v[236:239], v[80:83]
	v_mfma_f32_16x16x32_bf16 v[72:75], v[154:157], v[236:239], v[72:75]
	v_mfma_f32_16x16x32_bf16 v[128:131], v[146:149], v[216:219], v[128:131]
	v_mfma_f32_16x16x32_bf16 v[120:123], v[158:161], v[216:219], v[120:123]
	v_mfma_f32_16x16x32_bf16 v[112:115], v[146:149], v[224:227], v[112:115]
	v_mfma_f32_16x16x32_bf16 v[104:107], v[158:161], v[224:227], v[104:107]
	v_mfma_f32_16x16x32_bf16 v[96:99], v[146:149], v[232:235], v[96:99]
	v_mfma_f32_16x16x32_bf16 v[88:91], v[158:161], v[232:235], v[88:91]
	v_mfma_f32_16x16x32_bf16 v[80:83], v[146:149], v[240:243], v[80:83]
	v_mfma_f32_16x16x32_bf16 v[72:75], v[158:161], v[240:243], v[72:75]
	s_setprio 0
	s_setprio 1
	v_mfma_f32_16x16x32_bf16 v[124:127], v[174:177], v[212:215], v[124:127]
	v_mfma_f32_16x16x32_bf16 v[116:119], v[204:207], v[212:215], v[116:119]
	v_mfma_f32_16x16x32_bf16 v[108:111], v[174:177], v[220:223], v[108:111]
	v_mfma_f32_16x16x32_bf16 v[100:103], v[204:207], v[220:223], v[100:103]
	v_mfma_f32_16x16x32_bf16 v[92:95], v[174:177], v[228:231], v[92:95]
	v_mfma_f32_16x16x32_bf16 v[84:87], v[204:207], v[228:231], v[84:87]
	v_mfma_f32_16x16x32_bf16 v[76:79], v[174:177], v[236:239], v[76:79]
	v_mfma_f32_16x16x32_bf16 v[68:71], v[204:207], v[236:239], v[68:71]
	v_mfma_f32_16x16x32_bf16 v[124:127], v[178:181], v[216:219], v[124:127]
	v_mfma_f32_16x16x32_bf16 v[116:119], v[208:211], v[216:219], v[116:119]
	v_mfma_f32_16x16x32_bf16 v[108:111], v[178:181], v[224:227], v[108:111]
	v_mfma_f32_16x16x32_bf16 v[100:103], v[208:211], v[224:227], v[100:103]
	v_mfma_f32_16x16x32_bf16 v[92:95], v[178:181], v[232:235], v[92:95]
	v_mfma_f32_16x16x32_bf16 v[84:87], v[208:211], v[232:235], v[84:87]
	v_mfma_f32_16x16x32_bf16 v[76:79], v[178:181], v[240:243], v[76:79]
	v_mfma_f32_16x16x32_bf16 v[68:71], v[208:211], v[240:243], v[68:71]
	s_setprio 0
	s_barrier
	s_add_i32 s61, s61, s42
	s_mov_b32 m0, s61
	ds_read_b128 v[212:215], v153 offset:16384
	ds_read_b128 v[216:219], v153 offset:17408
	ds_read_b128 v[220:223], v153 offset:18432
	ds_read_b128 v[224:227], v153 offset:19456
	ds_read_b128 v[228:231], v153 offset:20480
	ds_read_b128 v[232:235], v153 offset:21504
	ds_read_b128 v[236:239], v153 offset:22528
	ds_read_b128 v[240:243], v153 offset:23552
	global_load_lds_dwordx4 v2, s[38:39]
	s_add_i32 m0, s61, 0x2000
	s_add_u32 s62, s38, 0x80000
	s_addc_u32 s63, s39, 0
	s_add_i32 s61, s64, s42
	global_load_lds_dwordx4 v132, s[38:39]
	s_mov_b32 m0, s61
	s_nop 0
	global_load_lds_dwordx4 v2, s[62:63]
	s_add_i32 m0, s61, 0x2000
	s_nop 0
	global_load_lds_dwordx4 v132, s[62:63]
	s_nop 0
	s_nop 0
	s_nop 0
	s_nop 0
	s_nop 0
	s_nop 0
	s_nop 0
	s_waitcnt vmcnt(6)
	s_waitcnt lgkmcnt(0)
	s_barrier
	s_setprio 1
	s_waitcnt lgkmcnt(0)
	v_mfma_f32_16x16x32_bf16 v[64:67], v[142:145], v[212:215], v[64:67]
	v_mfma_f32_16x16x32_bf16 v[56:59], v[154:157], v[212:215], v[56:59]
	v_mfma_f32_16x16x32_bf16 v[48:51], v[142:145], v[220:223], v[48:51]
	s_mov_b32 m0, s47
	v_mfma_f32_16x16x32_bf16 v[40:43], v[154:157], v[220:223], v[40:43]
	global_load_lds_dwordx4 v136, s[40:41]
	v_mfma_f32_16x16x32_bf16 v[32:35], v[142:145], v[228:231], v[32:35]
	v_mfma_f32_16x16x32_bf16 v[24:27], v[154:157], v[228:231], v[24:27]
	v_mfma_f32_16x16x32_bf16 v[16:19], v[142:145], v[236:239], v[16:19]
	v_mfma_f32_16x16x32_bf16 v[8:11], v[154:157], v[236:239], v[8:11]
	v_mfma_f32_16x16x32_bf16 v[64:67], v[146:149], v[216:219], v[64:67]
	v_mfma_f32_16x16x32_bf16 v[56:59], v[158:161], v[216:219], v[56:59]
	v_mfma_f32_16x16x32_bf16 v[48:51], v[146:149], v[224:227], v[48:51]
	s_mov_b32 m0, s48
	v_mfma_f32_16x16x32_bf16 v[40:43], v[158:161], v[224:227], v[40:43]
	global_load_lds_dwordx4 v134, s[40:41]
	v_mfma_f32_16x16x32_bf16 v[32:35], v[146:149], v[232:235], v[32:35]
	v_mfma_f32_16x16x32_bf16 v[24:27], v[158:161], v[232:235], v[24:27]
	v_mfma_f32_16x16x32_bf16 v[16:19], v[146:149], v[240:243], v[16:19]
	v_mfma_f32_16x16x32_bf16 v[8:11], v[158:161], v[240:243], v[8:11]
	s_setprio 0
	s_setprio 1
	v_mfma_f32_16x16x32_bf16 v[60:63], v[174:177], v[212:215], v[60:63]
	v_mfma_f32_16x16x32_bf16 v[52:55], v[204:207], v[212:215], v[52:55]
	v_mfma_f32_16x16x32_bf16 v[44:47], v[174:177], v[220:223], v[44:47]
	v_mfma_f32_16x16x32_bf16 v[36:39], v[204:207], v[220:223], v[36:39]
	v_mfma_f32_16x16x32_bf16 v[28:31], v[174:177], v[228:231], v[28:31]
	v_mfma_f32_16x16x32_bf16 v[20:23], v[204:207], v[228:231], v[20:23]
	v_mfma_f32_16x16x32_bf16 v[12:15], v[174:177], v[236:239], v[12:15]
	v_mfma_f32_16x16x32_bf16 v[4:7], v[204:207], v[236:239], v[4:7]
	v_mfma_f32_16x16x32_bf16 v[60:63], v[178:181], v[216:219], v[60:63]
	v_mfma_f32_16x16x32_bf16 v[52:55], v[208:211], v[216:219], v[52:55]
	v_mfma_f32_16x16x32_bf16 v[44:47], v[178:181], v[224:227], v[44:47]
	v_mfma_f32_16x16x32_bf16 v[36:39], v[208:211], v[224:227], v[36:39]
	v_mfma_f32_16x16x32_bf16 v[28:31], v[178:181], v[232:235], v[28:31]
	v_mfma_f32_16x16x32_bf16 v[20:23], v[208:211], v[232:235], v[20:23]
	v_mfma_f32_16x16x32_bf16 v[12:15], v[178:181], v[240:243], v[12:15]
	v_mfma_f32_16x16x32_bf16 v[4:7], v[208:211], v[240:243], v[4:7]
	s_setprio 0
	s_barrier
; #define PG8_STAGE(bufoff, gbase, voff) do { _Pragma("unroll") for (int _i = 0; _i < 2; ++_i) \
;         __builtin_amdgcn_global_load_lds((const unsigned*)((const char*)(gbase) + (voff)[_i]), (PG8_LAS unsigned*)(lds + (bufoff) + ldsw + _i * 8192), 16, 0, 0); } while (0)
; #define PG8_LDA(dst, b, h) do { _Pragma("unroll") for (int m = 0; m < 4; ++m) _Pragma("unroll") for (int k = 0; k < 2; ++k) dst[m][k] = *(const PG8_LAS bf16x8*)(lds + PG8_SA(b, h) + aoff + m * 2048 + k * 1024); } while (0)
; #define PG8_LDB(dst, b, h) do { _Pragma("unroll") for (int n = 0; n < 2; ++n) _Pragma("unroll") for (int k = 0; k < 2; ++k) dst[n][k] = *(const PG8_LAS bf16x8*)(lds + PG8_SB(b, h) + boff + n * 2048 + k * 1024); } while (0)
; #define PG8_MMA(ai, bj, At, Bt) do { __builtin_amdgcn_s_setprio(1); _Pragma("unroll") for (int m = 0; m < 4; ++m) _Pragma("unroll") for (int n = 0; n < 2; ++n) _Pragma("unroll") for (int k = 0; k < 2; ++k) \
;         acc[ai][bj][m][n] = __builtin_amdgcn_mfma_f32_16x16x32_bf16(Bt[n][k], At[m][k], acc[ai][bj][m][n], 0, 0, 0); __builtin_amdgcn_s_setprio(0); } while (0)
; #define PG8_WAIT_V(n) asm volatile("s_waitcnt vmcnt(" #n ")" ::: "memory")
; #define PG8_WAIT_L(n) asm volatile("s_waitcnt lgkmcnt(" #n ")" ::: "memory")
; #define PG8_BAR __builtin_amdgcn_s_barrier()
; #define PG8_SCHED __builtin_amdgcn_sched_barrier(0)
; template <class Epi, class Sched, bool ALIGN_EPI = false, bool SP2 = false>
; __device__ __forceinline__ void gemm_phase(PG8_LAS unsigned char* lds, const Gemm g, const Sched& S, const Epi& E) {
;     ...
;             PG8_LDB(B0, 1, 0); PG8_LDB(B1, 1, 1); PG8_SCHED; PG8_LDA(At, 1, 0); PG8_STAGE(PG8_SA(0, 1), a2 + hstep, voffA);
;             PG8_WAIT_V(8); PG8_WAIT_L(0); PG8_BAR; PG8_MMA(0, 0, At, B0); PG8_MMA(0, 1, At, B1); PG8_BAR; PG8_SCHED;
;             PG8_LDA(At, 1, 1); PG8_STAGE(PG8_SB(1, 0), b3, voffB); PG8_STAGE(PG8_SB(1, 1), b3 + hstep, voffB); PG8_STAGE(PG8_SA(1, 0), a3, voffA);
;             PG8_WAIT_V(8); PG8_WAIT_L(0); PG8_BAR; PG8_MMA(1, 0, At, B0); PG8_MMA(1, 1, At, B1); PG8_BAR; PG8_SCHED;
	s_add_i32 s61, 0, 0x18000
	s_add_i32 s62, 0, 0x1c000
	v_add_u32_e32 v158, s61, v150
	v_add_u32_e32 v164, s62, v150
	ds_read_b128 v[142:145], v158
	ds_read_b128 v[146:149], v158 offset:1024
	ds_read_b128 v[154:157], v158 offset:2048
	ds_read_b128 v[158:161], v158 offset:3072
	ds_read_b128 v[174:177], v164
	ds_read_b128 v[178:181], v164 offset:1024
	ds_read_b128 v[204:207], v164 offset:2048
	ds_read_b128 v[208:211], v164 offset:3072
	s_add_u32 s100, s40, 0x80
	s_addc_u32 s101, s41, 0
	s_add_u32 s40, s40, 0x80000
	s_addc_u32 s41, s41, 0
	s_mov_b32 m0, s49
	ds_read_b128 v[212:215], v153 offset:32768
	ds_read_b128 v[216:219], v153 offset:33792
	ds_read_b128 v[220:223], v153 offset:34816
	ds_read_b128 v[224:227], v153 offset:35840
	ds_read_b128 v[228:231], v153 offset:36864
	ds_read_b128 v[232:235], v153 offset:37888
	ds_read_b128 v[236:239], v153 offset:38912
	ds_read_b128 v[240:243], v153 offset:39936
	global_load_lds_dwordx4 v136, s[40:41]
	s_waitcnt vmcnt(7)
	s_waitcnt lgkmcnt(0)
	s_barrier
	s_setprio 1
	s_waitcnt lgkmcnt(0)
	v_mfma_f32_16x16x32_bf16 v[128:131], v[142:145], v[212:215], v[128:131]
	v_mfma_f32_16x16x32_bf16 v[120:123], v[154:157], v[212:215], v[120:123]
	v_mfma_f32_16x16x32_bf16 v[112:115], v[142:145], v[220:223], v[112:115]
	s_mov_b32 m0, s50
	v_mfma_f32_16x16x32_bf16 v[104:107], v[154:157], v[220:223], v[104:107]
	global_load_lds_dwordx4 v134, s[40:41]
	v_mfma_f32_16x16x32_bf16 v[96:99], v[142:145], v[228:231], v[96:99]
	v_mfma_f32_16x16x32_bf16 v[88:91], v[154:157], v[228:231], v[88:91]
	v_mfma_f32_16x16x32_bf16 v[80:83], v[142:145], v[236:239], v[80:83]
	v_mfma_f32_16x16x32_bf16 v[72:75], v[154:157], v[236:239], v[72:75]
	v_mfma_f32_16x16x32_bf16 v[128:131], v[146:149], v[216:219], v[128:131]
	v_mfma_f32_16x16x32_bf16 v[120:123], v[158:161], v[216:219], v[120:123]
	v_mfma_f32_16x16x32_bf16 v[112:115], v[146:149], v[224:227], v[112:115]
	v_mfma_f32_16x16x32_bf16 v[104:107], v[158:161], v[224:227], v[104:107]
	v_mfma_f32_16x16x32_bf16 v[96:99], v[146:149], v[232:235], v[96:99]
	v_mfma_f32_16x16x32_bf16 v[88:91], v[158:161], v[232:235], v[88:91]
	v_mfma_f32_16x16x32_bf16 v[80:83], v[146:149], v[240:243], v[80:83]
	v_mfma_f32_16x16x32_bf16 v[72:75], v[158:161], v[240:243], v[72:75]
	s_setprio 0
	s_setprio 1
	v_mfma_f32_16x16x32_bf16 v[124:127], v[174:177], v[212:215], v[124:127]
	v_mfma_f32_16x16x32_bf16 v[116:119], v[204:207], v[212:215], v[116:119]
	v_mfma_f32_16x16x32_bf16 v[108:111], v[174:177], v[220:223], v[108:111]
	v_mfma_f32_16x16x32_bf16 v[100:103], v[204:207], v[220:223], v[100:103]
	v_mfma_f32_16x16x32_bf16 v[92:95], v[174:177], v[228:231], v[92:95]
	v_mfma_f32_16x16x32_bf16 v[84:87], v[204:207], v[228:231], v[84:87]
	v_mfma_f32_16x16x32_bf16 v[76:79], v[174:177], v[236:239], v[76:79]
	v_mfma_f32_16x16x32_bf16 v[68:71], v[204:207], v[236:239], v[68:71]
	v_mfma_f32_16x16x32_bf16 v[124:127], v[178:181], v[216:219], v[124:127]
	v_mfma_f32_16x16x32_bf16 v[116:119], v[208:211], v[216:219], v[116:119]
	v_mfma_f32_16x16x32_bf16 v[108:111], v[178:181], v[224:227], v[108:111]
	v_mfma_f32_16x16x32_bf16 v[100:103], v[208:211], v[224:227], v[100:103]
	v_mfma_f32_16x16x32_bf16 v[92:95], v[178:181], v[232:235], v[92:95]
	v_mfma_f32_16x16x32_bf16 v[84:87], v[208:211], v[232:235], v[84:87]
	v_mfma_f32_16x16x32_bf16 v[76:79], v[178:181], v[240:243], v[76:79]
	v_mfma_f32_16x16x32_bf16 v[68:71], v[208:211], v[240:243], v[68:71]
	s_setprio 0
	s_barrier
	s_add_i32 s40, s61, s42
	s_add_i32 m0, s40, 0xffffff80
	ds_read_b128 v[212:215], v153 offset:49152
	ds_read_b128 v[216:219], v153 offset:50176
	ds_read_b128 v[220:223], v153 offset:51200
	ds_read_b128 v[224:227], v153 offset:52224
	ds_read_b128 v[228:231], v153 offset:53248
	ds_read_b128 v[232:235], v153 offset:54272
	ds_read_b128 v[236:239], v153 offset:55296
	ds_read_b128 v[240:243], v153 offset:56320
	global_load_lds_dwordx4 v2, s[38:39] offset:128
	s_add_i32 m0, s40, 0x1f80
	s_add_i32 s40, s62, s42
	global_load_lds_dwordx4 v132, s[38:39] offset:128
	s_add_u32 s38, s38, 0x80080
	s_addc_u32 s39, s39, 0
	s_mov_b32 m0, s40
	s_nop 0
	global_load_lds_dwordx4 v2, s[38:39]
	s_add_i32 m0, s40, 0x2000
	s_nop 0
	global_load_lds_dwordx4 v132, s[38:39]
	s_waitcnt vmcnt(6)
	s_waitcnt lgkmcnt(0)
	s_barrier
	s_setprio 1
	s_waitcnt lgkmcnt(0)
	v_mfma_f32_16x16x32_bf16 v[64:67], v[142:145], v[212:215], v[64:67]
	v_mfma_f32_16x16x32_bf16 v[56:59], v[154:157], v[212:215], v[56:59]
	v_mfma_f32_16x16x32_bf16 v[48:51], v[142:145], v[220:223], v[48:51]
	s_mov_b32 m0, s51
	v_mfma_f32_16x16x32_bf16 v[40:43], v[154:157], v[220:223], v[40:43]
	global_load_lds_dwordx4 v136, s[100:101]
	v_mfma_f32_16x16x32_bf16 v[32:35], v[142:145], v[228:231], v[32:35]
	v_mfma_f32_16x16x32_bf16 v[24:27], v[154:157], v[228:231], v[24:27]
	v_mfma_f32_16x16x32_bf16 v[16:19], v[142:145], v[236:239], v[16:19]
	v_mfma_f32_16x16x32_bf16 v[8:11], v[154:157], v[236:239], v[8:11]
	v_mfma_f32_16x16x32_bf16 v[64:67], v[146:149], v[216:219], v[64:67]
	v_mfma_f32_16x16x32_bf16 v[56:59], v[158:161], v[216:219], v[56:59]
	v_mfma_f32_16x16x32_bf16 v[48:51], v[146:149], v[224:227], v[48:51]
	s_mov_b32 m0, s53
	v_mfma_f32_16x16x32_bf16 v[40:43], v[158:161], v[224:227], v[40:43]
	global_load_lds_dwordx4 v134, s[100:101]
	v_mfma_f32_16x16x32_bf16 v[32:35], v[146:149], v[232:235], v[32:35]
	v_mfma_f32_16x16x32_bf16 v[24:27], v[158:161], v[232:235], v[24:27]
	v_mfma_f32_16x16x32_bf16 v[16:19], v[146:149], v[240:243], v[16:19]
	v_mfma_f32_16x16x32_bf16 v[8:11], v[158:161], v[240:243], v[8:11]
	s_setprio 0
	s_setprio 1
	v_mfma_f32_16x16x32_bf16 v[60:63], v[174:177], v[212:215], v[60:63]
	v_mfma_f32_16x16x32_bf16 v[52:55], v[204:207], v[212:215], v[52:55]
	v_mfma_f32_16x16x32_bf16 v[44:47], v[174:177], v[220:223], v[44:47]
	v_mfma_f32_16x16x32_bf16 v[36:39], v[204:207], v[220:223], v[36:39]
	v_mfma_f32_16x16x32_bf16 v[28:31], v[174:177], v[228:231], v[28:31]
	v_mfma_f32_16x16x32_bf16 v[20:23], v[204:207], v[228:231], v[20:23]
	v_mfma_f32_16x16x32_bf16 v[12:15], v[174:177], v[236:239], v[12:15]
	v_mfma_f32_16x16x32_bf16 v[4:7], v[204:207], v[236:239], v[4:7]
	v_mfma_f32_16x16x32_bf16 v[60:63], v[178:181], v[216:219], v[60:63]
	v_mfma_f32_16x16x32_bf16 v[52:55], v[208:211], v[216:219], v[52:55]
	v_mfma_f32_16x16x32_bf16 v[44:47], v[178:181], v[224:227], v[44:47]
	v_mfma_f32_16x16x32_bf16 v[36:39], v[208:211], v[224:227], v[36:39]
	v_mfma_f32_16x16x32_bf16 v[28:31], v[178:181], v[232:235], v[28:31]
	v_mfma_f32_16x16x32_bf16 v[20:23], v[208:211], v[232:235], v[20:23]
	v_mfma_f32_16x16x32_bf16 v[12:15], v[178:181], v[240:243], v[12:15]
	v_mfma_f32_16x16x32_bf16 v[4:7], v[208:211], v[240:243], v[4:7]
	s_setprio 0
	s_barrier
	s_add_i32 s60, s60, 2
	s_add_u32 s36, s36, 0x100
	s_addc_u32 s37, s37, 0
	s_add_u32 s58, s58, 0x100
	s_addc_u32 s59, s59, 0
	s_cmp_gt_u32 s60, 29
	s_cbranch_scc0 .LBB0_301
	s_and_b64 vcc, exec, s[8:9]
	s_cbranch_vccz .LBB0_304
	s_barrier

; #define PG8_STAGE(bufoff, gbase, voff) do { _Pragma("unroll") for (int _i = 0; _i < 2; ++_i) \
;         __builtin_amdgcn_global_load_lds((const unsigned*)((const char*)(gbase) + (voff)[_i]), (PG8_LAS unsigned*)(lds + (bufoff) + ldsw + _i * 8192), 16, 0, 0); } while (0)
; #define PG8_LDA(dst, b, h) do { _Pragma("unroll") for (int m = 0; m < 4; ++m) _Pragma("unroll") for (int k = 0; k < 2; ++k) dst[m][k] = *(const PG8_LAS bf16x8*)(lds + PG8_SA(b, h) + aoff + m * 2048 + k * 1024); } while (0)
; #define PG8_LDB(dst, b, h) do { _Pragma("unroll") for (int n = 0; n < 2; ++n) _Pragma("unroll") for (int k = 0; k < 2; ++k) dst[n][k] = *(const PG8_LAS bf16x8*)(lds + PG8_SB(b, h) + boff + n * 2048 + k * 1024); } while (0)
; #define PG8_MMA(ai, bj, At, Bt) do { __builtin_amdgcn_s_setprio(1); _Pragma("unroll") for (int m = 0; m < 4; ++m) _Pragma("unroll") for (int n = 0; n < 2; ++n) _Pragma("unroll") for (int k = 0; k < 2; ++k) \
;         acc[ai][bj][m][n] = __builtin_amdgcn_mfma_f32_16x16x32_bf16(Bt[n][k], At[m][k], acc[ai][bj][m][n], 0, 0, 0); __builtin_amdgcn_s_setprio(0); } while (0)
; #define PG8_WAIT_V(n) asm volatile("s_waitcnt vmcnt(" #n ")" ::: "memory")
; #define PG8_WAIT_L(n) asm volatile("s_waitcnt lgkmcnt(" #n ")" ::: "memory")
; template <class Epi, class Sched, bool ALIGN_EPI = false, bool SP2 = false>
; __device__ __forceinline__ void gemm_phase(PG8_LAS unsigned char* lds, const Gemm g, const Sched& S, const Epi& E) {
;     ...
;             const bool last = (t == nt - 2);
;             const char* a1 = cA + (size_t)(t + 1) * kstep;
;             const char* a2 = last ? nA : cA + (size_t)(t + 2) * kstep; const char* b2 = last ? nB : cB + (size_t)(t + 2) * kstep;
;             const char* a3 = a2 + kstep; const char* b3 = b2 + kstep;
;             if (last && has_next) S.a_ready(nxt);
;             if constexpr (SP2) {
;             PG8_LDB(B0, 0, 0); PG8_LDB(B1, 0, 1); PG8_SCHED; PG8_LDA(At, 0, 0); PG8_STAGE(PG8_SA(1, 1), a1 + hstep, voffA);
;             PG8_WAIT_V(8); PG8_WAIT_L(0); PG8_BAR; PG8_MMA(0, 0, At, B0); PG8_MMA(0, 1, At, B1); PG8_BAR; PG8_SCHED;
;             PG8_LDA(At, 0, 1); PG8_STAGE(PG8_SB(0, 0), b2, voffB); PG8_STAGE(PG8_SB(0, 1), b2 + hstep, voffB); PG8_STAGE(PG8_SA(0, 0), a2, voffA);
;             PG8_WAIT_V(8); PG8_WAIT_L(0); PG8_BAR; PG8_MMA(1, 0, At, B0); PG8_MMA(1, 1, At, B1); PG8_BAR; PG8_SCHED;
.LBB0_575:
	s_add_u32 s36, s34, 0x100
	s_addc_u32 s37, s35, 0
	s_add_i32 s64, 0, 0x10000
	s_cmpk_eq_i32 s63, 0x52
	s_cselect_b32 s41, s5, s37
	s_cselect_b32 s40, s4, s36
	v_add_u32_e32 v135, s64, v173
	s_cselect_b32 s39, s31, s62
	s_cselect_b32 s38, s30, s61
	s_add_i32 s65, 0, 0x14000
	ds_read_b128 v[142:145], v135
	ds_read_b128 v[146:149], v135 offset:1024
	ds_read_b128 v[150:153], v135 offset:2048
	ds_read_b128 v[154:157], v135 offset:3072
	v_add_u32_e32 v135, s65, v173
	ds_read_b128 v[158:161], v135
	ds_read_b128 v[174:177], v135 offset:1024
	ds_read_b128 v[180:183], v135 offset:2048
	ds_read_b128 v[204:207], v135 offset:3072
	v_lshl_add_u64 v[162:163], s[34:35], 0, v[138:139]
	s_add_i32 m0, s47, 0xc000
	ds_read_b128 v[208:211], v179
	ds_read_b128 v[212:215], v179 offset:1024
	ds_read_b128 v[216:219], v179 offset:2048
	ds_read_b128 v[220:223], v179 offset:3072
	ds_read_b128 v[224:227], v179 offset:4096
	ds_read_b128 v[228:231], v179 offset:5120
	ds_read_b128 v[232:235], v179 offset:6144
	ds_read_b128 v[236:239], v179 offset:7168
	global_load_lds_dwordx4 v[162:163], off
	v_lshl_add_u64 v[162:163], s[34:35], 0, v[140:141]
	s_nop 0
	s_waitcnt vmcnt(7)
	s_waitcnt lgkmcnt(0)
	s_barrier
	s_setprio 1
	s_waitcnt lgkmcnt(0)
	v_mfma_f32_16x16x32_bf16 v[128:131], v[142:145], v[208:211], v[128:131]
	v_mfma_f32_16x16x32_bf16 v[124:127], v[150:153], v[208:211], v[124:127]
	v_mfma_f32_16x16x32_bf16 v[112:115], v[142:145], v[216:219], v[112:115]
	s_add_i32 m0, s47, 0xe000
	v_mfma_f32_16x16x32_bf16 v[108:111], v[150:153], v[216:219], v[108:111]
	global_load_lds_dwordx4 v[162:163], off
	v_mfma_f32_16x16x32_bf16 v[96:99], v[142:145], v[224:227], v[96:99]
	v_mfma_f32_16x16x32_bf16 v[92:95], v[150:153], v[224:227], v[92:95]
	v_mfma_f32_16x16x32_bf16 v[80:83], v[142:145], v[232:235], v[80:83]
	v_mfma_f32_16x16x32_bf16 v[76:79], v[150:153], v[232:235], v[76:79]
	v_mfma_f32_16x16x32_bf16 v[128:131], v[146:149], v[212:215], v[128:131]
	v_mfma_f32_16x16x32_bf16 v[124:127], v[154:157], v[212:215], v[124:127]
	v_mfma_f32_16x16x32_bf16 v[112:115], v[146:149], v[220:223], v[112:115]
	v_mfma_f32_16x16x32_bf16 v[108:111], v[154:157], v[220:223], v[108:111]
	v_mfma_f32_16x16x32_bf16 v[96:99], v[146:149], v[228:231], v[96:99]
	v_mfma_f32_16x16x32_bf16 v[92:95], v[154:157], v[228:231], v[92:95]
	v_mfma_f32_16x16x32_bf16 v[80:83], v[146:149], v[236:239], v[80:83]
	v_mfma_f32_16x16x32_bf16 v[76:79], v[154:157], v[236:239], v[76:79]
	s_setprio 0
	s_setprio 1
	v_mfma_f32_16x16x32_bf16 v[120:123], v[158:161], v[208:211], v[120:123]
	v_mfma_f32_16x16x32_bf16 v[116:119], v[180:183], v[208:211], v[116:119]
	v_mfma_f32_16x16x32_bf16 v[104:107], v[158:161], v[216:219], v[104:107]
	v_mfma_f32_16x16x32_bf16 v[100:103], v[180:183], v[216:219], v[100:103]
	v_mfma_f32_16x16x32_bf16 v[88:91], v[158:161], v[224:227], v[88:91]
	v_mfma_f32_16x16x32_bf16 v[84:87], v[180:183], v[224:227], v[84:87]
	v_mfma_f32_16x16x32_bf16 v[72:75], v[158:161], v[232:235], v[72:75]
	v_mfma_f32_16x16x32_bf16 v[68:71], v[180:183], v[232:235], v[68:71]
	v_mfma_f32_16x16x32_bf16 v[120:123], v[174:177], v[212:215], v[120:123]
	v_mfma_f32_16x16x32_bf16 v[116:119], v[204:207], v[212:215], v[116:119]
	v_mfma_f32_16x16x32_bf16 v[104:107], v[174:177], v[220:223], v[104:107]
	v_mfma_f32_16x16x32_bf16 v[100:103], v[204:207], v[220:223], v[100:103]
	v_mfma_f32_16x16x32_bf16 v[88:91], v[174:177], v[228:231], v[88:91]
	v_mfma_f32_16x16x32_bf16 v[84:87], v[204:207], v[228:231], v[84:87]
	v_mfma_f32_16x16x32_bf16 v[72:75], v[174:177], v[236:239], v[72:75]
	v_mfma_f32_16x16x32_bf16 v[68:71], v[204:207], v[236:239], v[68:71]
	s_setprio 0
	s_barrier
	s_add_i32 s34, s64, s46
	s_mov_b32 m0, s34
	ds_read_b128 v[208:211], v179 offset:16384
	ds_read_b128 v[212:215], v179 offset:17408
	ds_read_b128 v[216:219], v179 offset:18432
	ds_read_b128 v[220:223], v179 offset:19456
	ds_read_b128 v[224:227], v179 offset:20480
	ds_read_b128 v[228:231], v179 offset:21504
	ds_read_b128 v[232:235], v179 offset:22528
	ds_read_b128 v[236:239], v179 offset:23552
	global_load_lds_dwordx4 v2, s[38:39]
	s_add_i32 m0, s34, 0x2000
	s_add_u32 s34, s38, 0x158000
	s_addc_u32 s35, s39, 0
	s_add_i32 s64, s65, s46
	global_load_lds_dwordx4 v132, s[38:39]
	s_mov_b32 m0, s64
	s_nop 0
	global_load_lds_dwordx4 v2, s[34:35]
	s_add_i32 m0, s64, 0x2000
	s_nop 0
	global_load_lds_dwordx4 v132, s[34:35]
	s_nop 0
	s_nop 0
	s_nop 0
	s_nop 0
	s_nop 0
	s_nop 0
	s_nop 0
	s_waitcnt vmcnt(6)
	s_waitcnt lgkmcnt(0)
	s_barrier
; #define PG8_STAGE(bufoff, gbase, voff) do { _Pragma("unroll") for (int _i = 0; _i < 2; ++_i) \
;         __builtin_amdgcn_global_load_lds((const unsigned*)((const char*)(gbase) + (voff)[_i]), (PG8_LAS unsigned*)(lds + (bufoff) + ldsw + _i * 8192), 16, 0, 0); } while (0)
; #define PG8_LDA(dst, b, h) do { _Pragma("unroll") for (int m = 0; m < 4; ++m) _Pragma("unroll") for (int k = 0; k < 2; ++k) dst[m][k] = *(const PG8_LAS bf16x8*)(lds + PG8_SA(b, h) + aoff + m * 2048 + k * 1024); } while (0)
; #define PG8_LDB(dst, b, h) do { _Pragma("unroll") for (int n = 0; n < 2; ++n) _Pragma("unroll") for (int k = 0; k < 2; ++k) dst[n][k] = *(const PG8_LAS bf16x8*)(lds + PG8_SB(b, h) + boff + n * 2048 + k * 1024); } while (0)
; #define PG8_MMA(ai, bj, At, Bt) do { __builtin_amdgcn_s_setprio(1); _Pragma("unroll") for (int m = 0; m < 4; ++m) _Pragma("unroll") for (int n = 0; n < 2; ++n) _Pragma("unroll") for (int k = 0; k < 2; ++k) \
;         acc[ai][bj][m][n] = __builtin_amdgcn_mfma_f32_16x16x32_bf16(Bt[n][k], At[m][k], acc[ai][bj][m][n], 0, 0, 0); __builtin_amdgcn_s_setprio(0); } while (0)
; #define PG8_WAIT_V(n) asm volatile("s_waitcnt vmcnt(" #n ")" ::: "memory")
; #define PG8_WAIT_L(n) asm volatile("s_waitcnt lgkmcnt(" #n ")" ::: "memory")
; #define PG8_BAR __builtin_amdgcn_s_barrier()
; #define PG8_SCHED __builtin_amdgcn_sched_barrier(0)
; template <class Epi, class Sched, bool ALIGN_EPI = false, bool SP2 = false>
; __device__ __forceinline__ void gemm_phase(PG8_LAS unsigned char* lds, const Gemm g, const Sched& S, const Epi& E) {
;     ...
;             PG8_WAIT_V(8); PG8_WAIT_L(0); PG8_BAR; PG8_MMA(1, 0, At, B0); PG8_MMA(1, 1, At, B1); PG8_BAR; PG8_SCHED;
;             PG8_LDB(B0, 1, 0); PG8_LDB(B1, 1, 1); PG8_SCHED; PG8_LDA(At, 1, 0); PG8_STAGE(PG8_SA(0, 1), a2 + hstep, voffA);
;             PG8_WAIT_V(8); PG8_WAIT_L(0); PG8_BAR; PG8_MMA(0, 0, At, B0); PG8_MMA(0, 1, At, B1); PG8_BAR; PG8_SCHED;
	s_setprio 1
	s_waitcnt lgkmcnt(0)
	v_mfma_f32_16x16x32_bf16 v[64:67], v[142:145], v[208:211], v[64:67]
	v_mfma_f32_16x16x32_bf16 v[60:63], v[150:153], v[208:211], v[60:63]
	v_mfma_f32_16x16x32_bf16 v[48:51], v[142:145], v[216:219], v[48:51]
	s_mov_b32 m0, s47
	v_mfma_f32_16x16x32_bf16 v[44:47], v[150:153], v[216:219], v[44:47]
	global_load_lds_dwordx4 v2, s[40:41]
	v_mfma_f32_16x16x32_bf16 v[32:35], v[142:145], v[224:227], v[32:35]
	v_mfma_f32_16x16x32_bf16 v[28:31], v[150:153], v[224:227], v[28:31]
	v_mfma_f32_16x16x32_bf16 v[16:19], v[142:145], v[232:235], v[16:19]
	v_mfma_f32_16x16x32_bf16 v[12:15], v[150:153], v[232:235], v[12:15]
	v_mfma_f32_16x16x32_bf16 v[64:67], v[146:149], v[212:215], v[64:67]
	v_mfma_f32_16x16x32_bf16 v[60:63], v[154:157], v[212:215], v[60:63]
	v_mfma_f32_16x16x32_bf16 v[48:51], v[146:149], v[220:223], v[48:51]
	s_mov_b32 m0, s48
	v_mfma_f32_16x16x32_bf16 v[44:47], v[154:157], v[220:223], v[44:47]
	global_load_lds_dwordx4 v132, s[40:41]
	v_mfma_f32_16x16x32_bf16 v[32:35], v[146:149], v[228:231], v[32:35]
	v_mfma_f32_16x16x32_bf16 v[28:31], v[154:157], v[228:231], v[28:31]
	v_mfma_f32_16x16x32_bf16 v[16:19], v[146:149], v[236:239], v[16:19]
	v_mfma_f32_16x16x32_bf16 v[12:15], v[154:157], v[236:239], v[12:15]
	s_setprio 0
	s_setprio 1
	v_mfma_f32_16x16x32_bf16 v[56:59], v[158:161], v[208:211], v[56:59]
	v_mfma_f32_16x16x32_bf16 v[52:55], v[180:183], v[208:211], v[52:55]
	v_mfma_f32_16x16x32_bf16 v[40:43], v[158:161], v[216:219], v[40:43]
	v_mfma_f32_16x16x32_bf16 v[36:39], v[180:183], v[216:219], v[36:39]
	v_mfma_f32_16x16x32_bf16 v[24:27], v[158:161], v[224:227], v[24:27]
	v_mfma_f32_16x16x32_bf16 v[20:23], v[180:183], v[224:227], v[20:23]
	v_mfma_f32_16x16x32_bf16 v[8:11], v[158:161], v[232:235], v[8:11]
	v_mfma_f32_16x16x32_bf16 v[4:7], v[180:183], v[232:235], v[4:7]
	v_mfma_f32_16x16x32_bf16 v[56:59], v[174:177], v[212:215], v[56:59]
	v_mfma_f32_16x16x32_bf16 v[52:55], v[204:207], v[212:215], v[52:55]
	v_mfma_f32_16x16x32_bf16 v[40:43], v[174:177], v[220:223], v[40:43]
	v_mfma_f32_16x16x32_bf16 v[36:39], v[204:207], v[220:223], v[36:39]
	v_mfma_f32_16x16x32_bf16 v[24:27], v[174:177], v[228:231], v[24:27]
	v_mfma_f32_16x16x32_bf16 v[20:23], v[204:207], v[228:231], v[20:23]
	v_mfma_f32_16x16x32_bf16 v[8:11], v[174:177], v[236:239], v[8:11]
	v_mfma_f32_16x16x32_bf16 v[4:7], v[204:207], v[236:239], v[4:7]
	s_setprio 0
	s_barrier
	s_add_i32 s64, 0, 0x18000
	v_add_u32_e32 v135, s64, v173
	s_add_i32 s65, 0, 0x1c000
	ds_read_b128 v[142:145], v135
	ds_read_b128 v[146:149], v135 offset:1024
	ds_read_b128 v[150:153], v135 offset:2048
	ds_read_b128 v[154:157], v135 offset:3072
	v_add_u32_e32 v135, s65, v173
	ds_read_b128 v[158:161], v135
	ds_read_b128 v[174:177], v135 offset:1024
	ds_read_b128 v[180:183], v135 offset:2048
	ds_read_b128 v[204:207], v135 offset:3072
	s_add_u32 s34, s40, 0x158000
	s_addc_u32 s35, s41, 0
	s_mov_b32 m0, s49
	ds_read_b128 v[208:211], v179 offset:32768
	ds_read_b128 v[212:215], v179 offset:33792
	ds_read_b128 v[216:219], v179 offset:34816
	ds_read_b128 v[220:223], v179 offset:35840
	ds_read_b128 v[224:227], v179 offset:36864
	ds_read_b128 v[228:231], v179 offset:37888
	ds_read_b128 v[232:235], v179 offset:38912
	ds_read_b128 v[236:239], v179 offset:39936
	global_load_lds_dwordx4 v2, s[34:35]
	s_waitcnt vmcnt(7)
	s_waitcnt lgkmcnt(0)
	s_barrier
	s_setprio 1
	s_waitcnt lgkmcnt(0)
	v_mfma_f32_16x16x32_bf16 v[128:131], v[142:145], v[208:211], v[128:131]
	v_mfma_f32_16x16x32_bf16 v[124:127], v[150:153], v[208:211], v[124:127]
	v_mfma_f32_16x16x32_bf16 v[112:115], v[142:145], v[216:219], v[112:115]
	s_mov_b32 m0, s50
	v_mfma_f32_16x16x32_bf16 v[108:111], v[150:153], v[216:219], v[108:111]
	global_load_lds_dwordx4 v132, s[34:35]
	v_mfma_f32_16x16x32_bf16 v[96:99], v[142:145], v[224:227], v[96:99]
	v_mfma_f32_16x16x32_bf16 v[92:95], v[150:153], v[224:227], v[92:95]
	v_mfma_f32_16x16x32_bf16 v[80:83], v[142:145], v[232:235], v[80:83]
	v_mfma_f32_16x16x32_bf16 v[76:79], v[150:153], v[232:235], v[76:79]
	v_mfma_f32_16x16x32_bf16 v[128:131], v[146:149], v[212:215], v[128:131]
	v_mfma_f32_16x16x32_bf16 v[124:127], v[154:157], v[212:215], v[124:127]
	v_mfma_f32_16x16x32_bf16 v[112:115], v[146:149], v[220:223], v[112:115]
	v_mfma_f32_16x16x32_bf16 v[108:111], v[154:157], v[220:223], v[108:111]
	v_mfma_f32_16x16x32_bf16 v[96:99], v[146:149], v[228:231], v[96:99]
	v_mfma_f32_16x16x32_bf16 v[92:95], v[154:157], v[228:231], v[92:95]
	v_mfma_f32_16x16x32_bf16 v[80:83], v[146:149], v[236:239], v[80:83]
	v_mfma_f32_16x16x32_bf16 v[76:79], v[154:157], v[236:239], v[76:79]
	s_setprio 0
	s_setprio 1
	v_mfma_f32_16x16x32_bf16 v[120:123], v[158:161], v[208:211], v[120:123]
	v_mfma_f32_16x16x32_bf16 v[116:119], v[180:183], v[208:211], v[116:119]
	v_mfma_f32_16x16x32_bf16 v[104:107], v[158:161], v[216:219], v[104:107]
	v_mfma_f32_16x16x32_bf16 v[100:103], v[180:183], v[216:219], v[100:103]
	v_mfma_f32_16x16x32_bf16 v[88:91], v[158:161], v[224:227], v[88:91]
	v_mfma_f32_16x16x32_bf16 v[84:87], v[180:183], v[224:227], v[84:87]
	v_mfma_f32_16x16x32_bf16 v[72:75], v[158:161], v[232:235], v[72:75]
	v_mfma_f32_16x16x32_bf16 v[68:71], v[180:183], v[232:235], v[68:71]
	v_mfma_f32_16x16x32_bf16 v[120:123], v[174:177], v[212:215], v[120:123]
	v_mfma_f32_16x16x32_bf16 v[116:119], v[204:207], v[212:215], v[116:119]
	v_mfma_f32_16x16x32_bf16 v[104:107], v[174:177], v[220:223], v[104:107]
	v_mfma_f32_16x16x32_bf16 v[100:103], v[204:207], v[220:223], v[100:103]
	v_mfma_f32_16x16x32_bf16 v[88:91], v[174:177], v[228:231], v[88:91]
	v_mfma_f32_16x16x32_bf16 v[84:87], v[204:207], v[228:231], v[84:87]
	v_mfma_f32_16x16x32_bf16 v[72:75], v[174:177], v[236:239], v[72:75]
	v_mfma_f32_16x16x32_bf16 v[68:71], v[204:207], v[236:239], v[68:71]
	s_setprio 0
	s_barrier
; #define PG8_STAGE(bufoff, gbase, voff) do { _Pragma("unroll") for (int _i = 0; _i < 2; ++_i) \
;         __builtin_amdgcn_global_load_lds((const unsigned*)((const char*)(gbase) + (voff)[_i]), (PG8_LAS unsigned*)(lds + (bufoff) + ldsw + _i * 8192), 16, 0, 0); } while (0)
; #define PG8_LDA(dst, b, h) do { _Pragma("unroll") for (int m = 0; m < 4; ++m) _Pragma("unroll") for (int k = 0; k < 2; ++k) dst[m][k] = *(const PG8_LAS bf16x8*)(lds + PG8_SA(b, h) + aoff + m * 2048 + k * 1024); } while (0)
; #define PG8_MMA(ai, bj, At, Bt) do { __builtin_amdgcn_s_setprio(1); _Pragma("unroll") for (int m = 0; m < 4; ++m) _Pragma("unroll") for (int n = 0; n < 2; ++n) _Pragma("unroll") for (int k = 0; k < 2; ++k) \
;         acc[ai][bj][m][n] = __builtin_amdgcn_mfma_f32_16x16x32_bf16(Bt[n][k], At[m][k], acc[ai][bj][m][n], 0, 0, 0); __builtin_amdgcn_s_setprio(0); } while (0)
; #define PG8_WAIT_V(n) asm volatile("s_waitcnt vmcnt(" #n ")" ::: "memory")
; #define PG8_WAIT_L(n) asm volatile("s_waitcnt lgkmcnt(" #n ")" ::: "memory")
; #define PG8_BAR __builtin_amdgcn_s_barrier()
; #define PG8_SCHED __builtin_amdgcn_sched_barrier(0)
; template <class Epi, class Sched, bool ALIGN_EPI = false, bool SP2 = false>
; __device__ __forceinline__ void gemm_phase(PG8_LAS unsigned char* lds, const Gemm g, const Sched& S, const Epi& E) {
;     ...
;             PG8_LDA(At, 1, 1); PG8_STAGE(PG8_SB(1, 0), b3, voffB); PG8_STAGE(PG8_SB(1, 1), b3 + hstep, voffB); PG8_STAGE(PG8_SA(1, 0), a3, voffA);
;             PG8_WAIT_V(8); PG8_WAIT_L(0); PG8_BAR; PG8_MMA(1, 0, At, B0); PG8_MMA(1, 1, At, B1); PG8_BAR; PG8_SCHED;
	s_add_i32 s34, s64, s46
	s_add_i32 m0, s34, 0xffffff80
	ds_read_b128 v[208:211], v179 offset:49152
	ds_read_b128 v[212:215], v179 offset:50176
	ds_read_b128 v[216:219], v179 offset:51200
	ds_read_b128 v[220:223], v179 offset:52224
	ds_read_b128 v[224:227], v179 offset:53248
	ds_read_b128 v[228:231], v179 offset:54272
	ds_read_b128 v[232:235], v179 offset:55296
	ds_read_b128 v[236:239], v179 offset:56320
	global_load_lds_dwordx4 v2, s[38:39] offset:128
	s_add_i32 m0, s34, 0x1f80
	s_add_u32 s34, s38, 0x158080
	s_addc_u32 s35, s39, 0
	global_load_lds_dwordx4 v132, s[38:39] offset:128
	s_add_i32 s38, s65, s46
	s_mov_b32 m0, s38
	s_nop 0
	global_load_lds_dwordx4 v2, s[34:35]
	s_add_i32 m0, s38, 0x2000
	s_nop 0
	global_load_lds_dwordx4 v132, s[34:35]
	s_waitcnt vmcnt(6)
	s_waitcnt lgkmcnt(0)
	s_barrier
	s_setprio 1
	s_waitcnt lgkmcnt(0)
	v_mfma_f32_16x16x32_bf16 v[64:67], v[142:145], v[208:211], v[64:67]
	v_mfma_f32_16x16x32_bf16 v[60:63], v[150:153], v[208:211], v[60:63]
	v_mfma_f32_16x16x32_bf16 v[48:51], v[142:145], v[216:219], v[48:51]
	s_add_i32 m0, s53, 0xffffff80
	v_mfma_f32_16x16x32_bf16 v[44:47], v[150:153], v[216:219], v[44:47]
	global_load_lds_dwordx4 v2, s[40:41] offset:128
	v_mfma_f32_16x16x32_bf16 v[32:35], v[142:145], v[224:227], v[32:35]
	v_mfma_f32_16x16x32_bf16 v[28:31], v[150:153], v[224:227], v[28:31]
	v_mfma_f32_16x16x32_bf16 v[16:19], v[142:145], v[232:235], v[16:19]
	v_mfma_f32_16x16x32_bf16 v[12:15], v[150:153], v[232:235], v[12:15]
	v_mfma_f32_16x16x32_bf16 v[64:67], v[146:149], v[212:215], v[64:67]
	v_mfma_f32_16x16x32_bf16 v[60:63], v[154:157], v[212:215], v[60:63]
	v_mfma_f32_16x16x32_bf16 v[48:51], v[146:149], v[220:223], v[48:51]
	s_add_i32 m0, s54, 0xffffff80
	v_mfma_f32_16x16x32_bf16 v[44:47], v[154:157], v[220:223], v[44:47]
	global_load_lds_dwordx4 v132, s[40:41] offset:128
	v_mfma_f32_16x16x32_bf16 v[32:35], v[146:149], v[228:231], v[32:35]
	v_mfma_f32_16x16x32_bf16 v[28:31], v[154:157], v[228:231], v[28:31]
	v_mfma_f32_16x16x32_bf16 v[16:19], v[146:149], v[236:239], v[16:19]
	v_mfma_f32_16x16x32_bf16 v[12:15], v[154:157], v[236:239], v[12:15]
	s_setprio 0
	s_setprio 1
	v_mfma_f32_16x16x32_bf16 v[56:59], v[158:161], v[208:211], v[56:59]
	v_mfma_f32_16x16x32_bf16 v[52:55], v[180:183], v[208:211], v[52:55]
	v_mfma_f32_16x16x32_bf16 v[40:43], v[158:161], v[216:219], v[40:43]
	v_mfma_f32_16x16x32_bf16 v[36:39], v[180:183], v[216:219], v[36:39]
	v_mfma_f32_16x16x32_bf16 v[24:27], v[158:161], v[224:227], v[24:27]
	v_mfma_f32_16x16x32_bf16 v[20:23], v[180:183], v[224:227], v[20:23]
	v_mfma_f32_16x16x32_bf16 v[8:11], v[158:161], v[232:235], v[8:11]
	v_mfma_f32_16x16x32_bf16 v[4:7], v[180:183], v[232:235], v[4:7]
	v_mfma_f32_16x16x32_bf16 v[56:59], v[174:177], v[212:215], v[56:59]
	v_mfma_f32_16x16x32_bf16 v[52:55], v[204:207], v[212:215], v[52:55]
	v_mfma_f32_16x16x32_bf16 v[40:43], v[174:177], v[220:223], v[40:43]
	v_mfma_f32_16x16x32_bf16 v[36:39], v[204:207], v[220:223], v[36:39]
	v_mfma_f32_16x16x32_bf16 v[24:27], v[174:177], v[228:231], v[24:27]
	v_mfma_f32_16x16x32_bf16 v[20:23], v[204:207], v[228:231], v[20:23]
	v_mfma_f32_16x16x32_bf16 v[8:11], v[174:177], v[236:239], v[8:11]
	v_mfma_f32_16x16x32_bf16 v[4:7], v[204:207], v[236:239], v[4:7]
	s_setprio 0
	s_barrier
	s_add_i32 s63, s63, 2
	s_add_u32 s61, s61, 0x100
	s_addc_u32 s62, s62, 0
	s_cmpk_gt_u32 s63, 0x53
	s_mov_b64 s[34:35], s[36:37]
	s_cbranch_scc0 .LBB0_575
	s_and_b64 vcc, exec, s[28:29]
	s_cbranch_vccz .LBB0_578
	s_barrier

; #define PG8_STAGE(bufoff, gbase, voff) do { _Pragma("unroll") for (int _i = 0; _i < 2; ++_i) \
;         __builtin_amdgcn_global_load_lds((const unsigned*)((const char*)(gbase) + (voff)[_i]), (PG8_LAS unsigned*)(lds + (bufoff) + ldsw + _i * 8192), 16, 0, 0); } while (0)
; #define PG8_LDA(dst, b, h) do { _Pragma("unroll") for (int m = 0; m < 4; ++m) _Pragma("unroll") for (int k = 0; k < 2; ++k) dst[m][k] = *(const PG8_LAS bf16x8*)(lds + PG8_SA(b, h) + aoff + m * 2048 + k * 1024); } while (0)
; #define PG8_LDB(dst, b, h) do { _Pragma("unroll") for (int n = 0; n < 2; ++n) _Pragma("unroll") for (int k = 0; k < 2; ++k) dst[n][k] = *(const PG8_LAS bf16x8*)(lds + PG8_SB(b, h) + boff + n * 2048 + k * 1024); } while (0)
; #define PG8_MMA(ai, bj, At, Bt) do { __builtin_amdgcn_s_setprio(1); _Pragma("unroll") for (int m = 0; m < 4; ++m) _Pragma("unroll") for (int n = 0; n < 2; ++n) _Pragma("unroll") for (int k = 0; k < 2; ++k) \
;         acc[ai][bj][m][n] = __builtin_amdgcn_mfma_f32_16x16x32_bf16(Bt[n][k], At[m][k], acc[ai][bj][m][n], 0, 0, 0); __builtin_amdgcn_s_setprio(0); } while (0)
; #define PG8_WAIT_V(n) asm volatile("s_waitcnt vmcnt(" #n ")" ::: "memory")
; #define PG8_WAIT_L(n) asm volatile("s_waitcnt lgkmcnt(" #n ")" ::: "memory")
; template <class Epi, class Sched, bool ALIGN_EPI = false, bool SP2 = false>
; __device__ __forceinline__ void gemm_phase(PG8_LAS unsigned char* lds, const Gemm g, const Sched& S, const Epi& E) {
;     ...
;             const bool last = (t == nt - 2);
;             const char* a1 = cA + (size_t)(t + 1) * kstep;
;             const char* a2 = last ? nA : cA + (size_t)(t + 2) * kstep; const char* b2 = last ? nB : cB + (size_t)(t + 2) * kstep;
;             const char* a3 = a2 + kstep; const char* b3 = b2 + kstep;
;             if (last && has_next) S.a_ready(nxt);
;             if constexpr (SP2) {
;             PG8_LDB(B0, 0, 0); PG8_LDB(B1, 0, 1); PG8_SCHED; PG8_LDA(At, 0, 0); PG8_STAGE(PG8_SA(1, 1), a1 + hstep, voffA);
;             PG8_WAIT_V(8); PG8_WAIT_L(0); PG8_BAR; PG8_MMA(0, 0, At, B0); PG8_MMA(0, 1, At, B1); PG8_BAR; PG8_SCHED;
;             PG8_LDA(At, 0, 1); PG8_STAGE(PG8_SB(0, 0), b2, voffB); PG8_STAGE(PG8_SB(0, 1), b2 + hstep, voffB); PG8_STAGE(PG8_SA(0, 0), a2, voffA);
;             PG8_WAIT_V(8); PG8_WAIT_L(0); PG8_BAR; PG8_MMA(1, 0, At, B0); PG8_MMA(1, 1, At, B1); PG8_BAR; PG8_SCHED;
.LBB0_674:
	s_add_u32 s42, s40, 0xfff80080
	s_addc_u32 s43, s41, -1
	s_add_i32 s64, 0, 0x10000
	s_cmp_eq_u32 s63, 28
	s_cselect_b32 s45, s5, s43
	s_cselect_b32 s44, s4, s42
	s_cselect_b32 s43, s37, s62
	s_cselect_b32 s42, s36, s35
	s_add_i32 s66, 0, 0x14000
	v_add_u32_e32 v144, s64, v173
	v_add_u32_e32 v162, s66, v173
	ds_read_b128 v[132:135], v144
	ds_read_b128 v[136:139], v144 offset:1024
	ds_read_b128 v[140:143], v144 offset:2048
	ds_read_b128 v[144:147], v144 offset:3072
	ds_read_b128 v[158:161], v162
	ds_read_b128 v[174:177], v162 offset:1024
	ds_read_b128 v[206:209], v162 offset:2048
	ds_read_b128 v[210:213], v162 offset:3072
	s_add_i32 m0, s39, 0xc000
	ds_read_b128 v[214:217], v204
	ds_read_b128 v[218:221], v204 offset:1024
	ds_read_b128 v[222:225], v204 offset:2048
	ds_read_b128 v[226:229], v204 offset:3072
	ds_read_b128 v[230:233], v204 offset:4096
	ds_read_b128 v[234:237], v204 offset:5120
	ds_read_b128 v[238:241], v204 offset:6144
	ds_read_b128 v[242:245], v204 offset:7168
	global_load_lds_dwordx4 v154, s[40:41]
	s_nop 0
	s_waitcnt vmcnt(7)
	s_waitcnt lgkmcnt(0)
	s_barrier
	s_setprio 1
	s_waitcnt lgkmcnt(0)
	v_mfma_f32_16x16x32_bf16 v[128:131], v[132:135], v[214:217], v[128:131]
	v_mfma_f32_16x16x32_bf16 v[124:127], v[140:143], v[214:217], v[124:127]
	v_mfma_f32_16x16x32_bf16 v[116:119], v[132:135], v[222:225], v[116:119]
	s_add_i32 m0, s39, 0xe000
	v_mfma_f32_16x16x32_bf16 v[108:111], v[140:143], v[222:225], v[108:111]
	global_load_lds_dwordx4 v156, s[40:41]
	v_mfma_f32_16x16x32_bf16 v[100:103], v[132:135], v[230:233], v[100:103]
	v_mfma_f32_16x16x32_bf16 v[92:95], v[140:143], v[230:233], v[92:95]
	v_mfma_f32_16x16x32_bf16 v[84:87], v[132:135], v[238:241], v[84:87]
	v_mfma_f32_16x16x32_bf16 v[76:79], v[140:143], v[238:241], v[76:79]
	v_mfma_f32_16x16x32_bf16 v[128:131], v[136:139], v[218:221], v[128:131]
	v_mfma_f32_16x16x32_bf16 v[124:127], v[144:147], v[218:221], v[124:127]
	v_mfma_f32_16x16x32_bf16 v[116:119], v[136:139], v[226:229], v[116:119]
	v_mfma_f32_16x16x32_bf16 v[108:111], v[144:147], v[226:229], v[108:111]
	v_mfma_f32_16x16x32_bf16 v[100:103], v[136:139], v[234:237], v[100:103]
	v_mfma_f32_16x16x32_bf16 v[92:95], v[144:147], v[234:237], v[92:95]
	v_mfma_f32_16x16x32_bf16 v[84:87], v[136:139], v[242:245], v[84:87]
	v_mfma_f32_16x16x32_bf16 v[76:79], v[144:147], v[242:245], v[76:79]
	s_setprio 0
	s_setprio 1
	v_mfma_f32_16x16x32_bf16 v[120:123], v[158:161], v[214:217], v[120:123]
	v_mfma_f32_16x16x32_bf16 v[112:115], v[206:209], v[214:217], v[112:115]
	v_mfma_f32_16x16x32_bf16 v[104:107], v[158:161], v[222:225], v[104:107]
	v_mfma_f32_16x16x32_bf16 v[96:99], v[206:209], v[222:225], v[96:99]
	v_mfma_f32_16x16x32_bf16 v[88:91], v[158:161], v[230:233], v[88:91]
	v_mfma_f32_16x16x32_bf16 v[80:83], v[206:209], v[230:233], v[80:83]
	v_mfma_f32_16x16x32_bf16 v[72:75], v[158:161], v[238:241], v[72:75]
	v_mfma_f32_16x16x32_bf16 v[68:71], v[206:209], v[238:241], v[68:71]
	v_mfma_f32_16x16x32_bf16 v[120:123], v[174:177], v[218:221], v[120:123]
	v_mfma_f32_16x16x32_bf16 v[112:115], v[210:213], v[218:221], v[112:115]
	v_mfma_f32_16x16x32_bf16 v[104:107], v[174:177], v[226:229], v[104:107]
	v_mfma_f32_16x16x32_bf16 v[96:99], v[210:213], v[226:229], v[96:99]
	v_mfma_f32_16x16x32_bf16 v[88:91], v[174:177], v[234:237], v[88:91]
	v_mfma_f32_16x16x32_bf16 v[80:83], v[210:213], v[234:237], v[80:83]
	v_mfma_f32_16x16x32_bf16 v[72:75], v[174:177], v[242:245], v[72:75]
	v_mfma_f32_16x16x32_bf16 v[68:71], v[210:213], v[242:245], v[68:71]
	s_setprio 0
	s_barrier
	s_add_i32 s64, s64, s46
	s_mov_b32 m0, s64
	ds_read_b128 v[214:217], v204 offset:16384
	ds_read_b128 v[218:221], v204 offset:17408
	ds_read_b128 v[222:225], v204 offset:18432
	ds_read_b128 v[226:229], v204 offset:19456
	ds_read_b128 v[230:233], v204 offset:20480
	ds_read_b128 v[234:237], v204 offset:21504
	ds_read_b128 v[238:241], v204 offset:22528
	ds_read_b128 v[242:245], v204 offset:23552
	global_load_lds_dwordx4 v2, s[42:43]
	s_add_i32 m0, s64, 0x2000
	s_add_u32 s64, s42, 0x80000
	s_addc_u32 s65, s43, 0
	s_add_i32 s66, s66, s46
	global_load_lds_dwordx4 v148, s[42:43]
	s_mov_b32 m0, s66
	s_nop 0
	global_load_lds_dwordx4 v2, s[64:65]
	s_add_i32 m0, s66, 0x2000
	s_nop 0
	global_load_lds_dwordx4 v148, s[64:65]
	s_nop 0
	s_nop 0
	s_nop 0
	s_nop 0
	s_nop 0
	s_nop 0
	s_nop 0
	s_waitcnt vmcnt(6)
	s_waitcnt lgkmcnt(0)
	s_barrier
	s_setprio 1
	s_waitcnt lgkmcnt(0)
	v_mfma_f32_16x16x32_bf16 v[64:67], v[132:135], v[214:217], v[64:67]
	v_mfma_f32_16x16x32_bf16 v[60:63], v[140:143], v[214:217], v[60:63]
	v_mfma_f32_16x16x32_bf16 v[52:55], v[132:135], v[222:225], v[52:55]
	s_mov_b32 m0, s39
	v_mfma_f32_16x16x32_bf16 v[44:47], v[140:143], v[222:225], v[44:47]
	global_load_lds_dwordx4 v152, s[44:45]
	v_mfma_f32_16x16x32_bf16 v[36:39], v[132:135], v[230:233], v[36:39]
	v_mfma_f32_16x16x32_bf16 v[28:31], v[140:143], v[230:233], v[28:31]
	v_mfma_f32_16x16x32_bf16 v[20:23], v[132:135], v[238:241], v[20:23]
	v_mfma_f32_16x16x32_bf16 v[12:15], v[140:143], v[238:241], v[12:15]
	v_mfma_f32_16x16x32_bf16 v[64:67], v[136:139], v[218:221], v[64:67]
	v_mfma_f32_16x16x32_bf16 v[60:63], v[144:147], v[218:221], v[60:63]
	v_mfma_f32_16x16x32_bf16 v[52:55], v[136:139], v[226:229], v[52:55]
	s_mov_b32 m0, s51
	v_mfma_f32_16x16x32_bf16 v[44:47], v[144:147], v[226:229], v[44:47]
	global_load_lds_dwordx4 v150, s[44:45]
	v_mfma_f32_16x16x32_bf16 v[36:39], v[136:139], v[234:237], v[36:39]
	v_mfma_f32_16x16x32_bf16 v[28:31], v[144:147], v[234:237], v[28:31]
	v_mfma_f32_16x16x32_bf16 v[20:23], v[136:139], v[242:245], v[20:23]
	v_mfma_f32_16x16x32_bf16 v[12:15], v[144:147], v[242:245], v[12:15]
	s_setprio 0
	s_setprio 1
	v_mfma_f32_16x16x32_bf16 v[56:59], v[158:161], v[214:217], v[56:59]
	v_mfma_f32_16x16x32_bf16 v[48:51], v[206:209], v[214:217], v[48:51]
	v_mfma_f32_16x16x32_bf16 v[40:43], v[158:161], v[222:225], v[40:43]
	v_mfma_f32_16x16x32_bf16 v[32:35], v[206:209], v[222:225], v[32:35]
	v_mfma_f32_16x16x32_bf16 v[24:27], v[158:161], v[230:233], v[24:27]
	v_mfma_f32_16x16x32_bf16 v[16:19], v[206:209], v[230:233], v[16:19]
	v_mfma_f32_16x16x32_bf16 v[8:11], v[158:161], v[238:241], v[8:11]
	v_mfma_f32_16x16x32_bf16 v[4:7], v[206:209], v[238:241], v[4:7]
	v_mfma_f32_16x16x32_bf16 v[56:59], v[174:177], v[218:221], v[56:59]
	v_mfma_f32_16x16x32_bf16 v[48:51], v[210:213], v[218:221], v[48:51]
	v_mfma_f32_16x16x32_bf16 v[40:43], v[174:177], v[226:229], v[40:43]
	v_mfma_f32_16x16x32_bf16 v[32:35], v[210:213], v[226:229], v[32:35]
	v_mfma_f32_16x16x32_bf16 v[24:27], v[174:177], v[234:237], v[24:27]
	v_mfma_f32_16x16x32_bf16 v[16:19], v[210:213], v[234:237], v[16:19]
	v_mfma_f32_16x16x32_bf16 v[8:11], v[174:177], v[242:245], v[8:11]
	v_mfma_f32_16x16x32_bf16 v[4:7], v[210:213], v[242:245], v[4:7]
	s_setprio 0
	s_barrier
; #define PG8_STAGE(bufoff, gbase, voff) do { _Pragma("unroll") for (int _i = 0; _i < 2; ++_i) \
;         __builtin_amdgcn_global_load_lds((const unsigned*)((const char*)(gbase) + (voff)[_i]), (PG8_LAS unsigned*)(lds + (bufoff) + ldsw + _i * 8192), 16, 0, 0); } while (0)
; #define PG8_LDA(dst, b, h) do { _Pragma("unroll") for (int m = 0; m < 4; ++m) _Pragma("unroll") for (int k = 0; k < 2; ++k) dst[m][k] = *(const PG8_LAS bf16x8*)(lds + PG8_SA(b, h) + aoff + m * 2048 + k * 1024); } while (0)
; #define PG8_LDB(dst, b, h) do { _Pragma("unroll") for (int n = 0; n < 2; ++n) _Pragma("unroll") for (int k = 0; k < 2; ++k) dst[n][k] = *(const PG8_LAS bf16x8*)(lds + PG8_SB(b, h) + boff + n * 2048 + k * 1024); } while (0)
; #define PG8_MMA(ai, bj, At, Bt) do { __builtin_amdgcn_s_setprio(1); _Pragma("unroll") for (int m = 0; m < 4; ++m) _Pragma("unroll") for (int n = 0; n < 2; ++n) _Pragma("unroll") for (int k = 0; k < 2; ++k) \
;         acc[ai][bj][m][n] = __builtin_amdgcn_mfma_f32_16x16x32_bf16(Bt[n][k], At[m][k], acc[ai][bj][m][n], 0, 0, 0); __builtin_amdgcn_s_setprio(0); } while (0)
; #define PG8_WAIT_V(n) asm volatile("s_waitcnt vmcnt(" #n ")" ::: "memory")
; #define PG8_WAIT_L(n) asm volatile("s_waitcnt lgkmcnt(" #n ")" ::: "memory")
; #define PG8_BAR __builtin_amdgcn_s_barrier()
; #define PG8_SCHED __builtin_amdgcn_sched_barrier(0)
; template <class Epi, class Sched, bool ALIGN_EPI = false, bool SP2 = false>
; __device__ __forceinline__ void gemm_phase(PG8_LAS unsigned char* lds, const Gemm g, const Sched& S, const Epi& E) {
;     ...
;             PG8_LDB(B0, 1, 0); PG8_LDB(B1, 1, 1); PG8_SCHED; PG8_LDA(At, 1, 0); PG8_STAGE(PG8_SA(0, 1), a2 + hstep, voffA);
;             PG8_WAIT_V(8); PG8_WAIT_L(0); PG8_BAR; PG8_MMA(0, 0, At, B0); PG8_MMA(0, 1, At, B1); PG8_BAR; PG8_SCHED;
;             PG8_LDA(At, 1, 1); PG8_STAGE(PG8_SB(1, 0), b3, voffB); PG8_STAGE(PG8_SB(1, 1), b3 + hstep, voffB); PG8_STAGE(PG8_SA(1, 0), a3, voffA);
;             PG8_WAIT_V(8); PG8_WAIT_L(0); PG8_BAR; PG8_MMA(1, 0, At, B0); PG8_MMA(1, 1, At, B1); PG8_BAR; PG8_SCHED;
	s_add_i32 s64, 0, 0x18000
	s_add_i32 s65, 0, 0x1c000
	v_add_u32_e32 v144, s64, v173
	v_add_u32_e32 v164, s65, v173
	ds_read_b128 v[132:135], v144
	ds_read_b128 v[136:139], v144 offset:1024
	ds_read_b128 v[140:143], v144 offset:2048
	ds_read_b128 v[144:147], v144 offset:3072
	ds_read_b128 v[158:161], v164
	ds_read_b128 v[174:177], v164 offset:1024
	ds_read_b128 v[206:209], v164 offset:2048
	ds_read_b128 v[210:213], v164 offset:3072
	s_add_u32 s100, s44, 0x80
	s_addc_u32 s101, s45, 0
	s_add_u32 s44, s44, 0x80000
	s_addc_u32 s45, s45, 0
	s_mov_b32 m0, s52
	ds_read_b128 v[214:217], v204 offset:32768
	ds_read_b128 v[218:221], v204 offset:33792
	ds_read_b128 v[222:225], v204 offset:34816
	ds_read_b128 v[226:229], v204 offset:35840
	ds_read_b128 v[230:233], v204 offset:36864
	ds_read_b128 v[234:237], v204 offset:37888
	ds_read_b128 v[238:241], v204 offset:38912
	ds_read_b128 v[242:245], v204 offset:39936
	global_load_lds_dwordx4 v152, s[44:45]
	s_waitcnt vmcnt(7)
	s_waitcnt lgkmcnt(0)
	s_barrier
	s_setprio 1
	s_waitcnt lgkmcnt(0)
	v_mfma_f32_16x16x32_bf16 v[128:131], v[132:135], v[214:217], v[128:131]
	v_mfma_f32_16x16x32_bf16 v[124:127], v[140:143], v[214:217], v[124:127]
	v_mfma_f32_16x16x32_bf16 v[116:119], v[132:135], v[222:225], v[116:119]
	s_mov_b32 m0, s53
	v_mfma_f32_16x16x32_bf16 v[108:111], v[140:143], v[222:225], v[108:111]
	global_load_lds_dwordx4 v150, s[44:45]
	v_mfma_f32_16x16x32_bf16 v[100:103], v[132:135], v[230:233], v[100:103]
	v_mfma_f32_16x16x32_bf16 v[92:95], v[140:143], v[230:233], v[92:95]
	v_mfma_f32_16x16x32_bf16 v[84:87], v[132:135], v[238:241], v[84:87]
	v_mfma_f32_16x16x32_bf16 v[76:79], v[140:143], v[238:241], v[76:79]
	v_mfma_f32_16x16x32_bf16 v[128:131], v[136:139], v[218:221], v[128:131]
	v_mfma_f32_16x16x32_bf16 v[124:127], v[144:147], v[218:221], v[124:127]
	v_mfma_f32_16x16x32_bf16 v[116:119], v[136:139], v[226:229], v[116:119]
	v_mfma_f32_16x16x32_bf16 v[108:111], v[144:147], v[226:229], v[108:111]
	v_mfma_f32_16x16x32_bf16 v[100:103], v[136:139], v[234:237], v[100:103]
	v_mfma_f32_16x16x32_bf16 v[92:95], v[144:147], v[234:237], v[92:95]
	v_mfma_f32_16x16x32_bf16 v[84:87], v[136:139], v[242:245], v[84:87]
	v_mfma_f32_16x16x32_bf16 v[76:79], v[144:147], v[242:245], v[76:79]
	s_setprio 0
	s_setprio 1
	v_mfma_f32_16x16x32_bf16 v[120:123], v[158:161], v[214:217], v[120:123]
	v_mfma_f32_16x16x32_bf16 v[112:115], v[206:209], v[214:217], v[112:115]
	v_mfma_f32_16x16x32_bf16 v[104:107], v[158:161], v[222:225], v[104:107]
	v_mfma_f32_16x16x32_bf16 v[96:99], v[206:209], v[222:225], v[96:99]
	v_mfma_f32_16x16x32_bf16 v[88:91], v[158:161], v[230:233], v[88:91]
	v_mfma_f32_16x16x32_bf16 v[80:83], v[206:209], v[230:233], v[80:83]
	v_mfma_f32_16x16x32_bf16 v[72:75], v[158:161], v[238:241], v[72:75]
	v_mfma_f32_16x16x32_bf16 v[68:71], v[206:209], v[238:241], v[68:71]
	v_mfma_f32_16x16x32_bf16 v[120:123], v[174:177], v[218:221], v[120:123]
	v_mfma_f32_16x16x32_bf16 v[112:115], v[210:213], v[218:221], v[112:115]
	v_mfma_f32_16x16x32_bf16 v[104:107], v[174:177], v[226:229], v[104:107]
	v_mfma_f32_16x16x32_bf16 v[96:99], v[210:213], v[226:229], v[96:99]
	v_mfma_f32_16x16x32_bf16 v[88:91], v[174:177], v[234:237], v[88:91]
	v_mfma_f32_16x16x32_bf16 v[80:83], v[210:213], v[234:237], v[80:83]
	v_mfma_f32_16x16x32_bf16 v[72:75], v[174:177], v[242:245], v[72:75]
	v_mfma_f32_16x16x32_bf16 v[68:71], v[210:213], v[242:245], v[68:71]
	s_setprio 0
	s_barrier
	s_add_i32 s44, s64, s46
	s_add_i32 m0, s44, 0xffffff80
	ds_read_b128 v[214:217], v204 offset:49152
	ds_read_b128 v[218:221], v204 offset:50176
	ds_read_b128 v[222:225], v204 offset:51200
	ds_read_b128 v[226:229], v204 offset:52224
	ds_read_b128 v[230:233], v204 offset:53248
	ds_read_b128 v[234:237], v204 offset:54272
	ds_read_b128 v[238:241], v204 offset:55296
	ds_read_b128 v[242:245], v204 offset:56320
	global_load_lds_dwordx4 v2, s[42:43] offset:128
	s_add_i32 m0, s44, 0x1f80
	s_add_i32 s44, s65, s46
	global_load_lds_dwordx4 v148, s[42:43] offset:128
	s_add_u32 s42, s42, 0x80080
	s_addc_u32 s43, s43, 0
	s_mov_b32 m0, s44
	s_nop 0
	global_load_lds_dwordx4 v2, s[42:43]
	s_add_i32 m0, s44, 0x2000
	s_nop 0
	global_load_lds_dwordx4 v148, s[42:43]
	s_waitcnt vmcnt(6)
	s_waitcnt lgkmcnt(0)
	s_barrier
	s_setprio 1
	s_waitcnt lgkmcnt(0)
	v_mfma_f32_16x16x32_bf16 v[64:67], v[132:135], v[214:217], v[64:67]
	v_mfma_f32_16x16x32_bf16 v[60:63], v[140:143], v[214:217], v[60:63]
	v_mfma_f32_16x16x32_bf16 v[52:55], v[132:135], v[222:225], v[52:55]
	s_mov_b32 m0, s54
	v_mfma_f32_16x16x32_bf16 v[44:47], v[140:143], v[222:225], v[44:47]
	global_load_lds_dwordx4 v152, s[100:101]
	v_mfma_f32_16x16x32_bf16 v[36:39], v[132:135], v[230:233], v[36:39]
	v_mfma_f32_16x16x32_bf16 v[28:31], v[140:143], v[230:233], v[28:31]
	v_mfma_f32_16x16x32_bf16 v[20:23], v[132:135], v[238:241], v[20:23]
	v_mfma_f32_16x16x32_bf16 v[12:15], v[140:143], v[238:241], v[12:15]
	v_mfma_f32_16x16x32_bf16 v[64:67], v[136:139], v[218:221], v[64:67]
	v_mfma_f32_16x16x32_bf16 v[60:63], v[144:147], v[218:221], v[60:63]
	v_mfma_f32_16x16x32_bf16 v[52:55], v[136:139], v[226:229], v[52:55]
	s_mov_b32 m0, s55
	v_mfma_f32_16x16x32_bf16 v[44:47], v[144:147], v[226:229], v[44:47]
	global_load_lds_dwordx4 v150, s[100:101]
	v_mfma_f32_16x16x32_bf16 v[36:39], v[136:139], v[234:237], v[36:39]
	v_mfma_f32_16x16x32_bf16 v[28:31], v[144:147], v[234:237], v[28:31]
	v_mfma_f32_16x16x32_bf16 v[20:23], v[136:139], v[242:245], v[20:23]
	v_mfma_f32_16x16x32_bf16 v[12:15], v[144:147], v[242:245], v[12:15]
	s_setprio 0
	s_setprio 1
	v_mfma_f32_16x16x32_bf16 v[56:59], v[158:161], v[214:217], v[56:59]
	v_mfma_f32_16x16x32_bf16 v[48:51], v[206:209], v[214:217], v[48:51]
	v_mfma_f32_16x16x32_bf16 v[40:43], v[158:161], v[222:225], v[40:43]
	v_mfma_f32_16x16x32_bf16 v[32:35], v[206:209], v[222:225], v[32:35]
	v_mfma_f32_16x16x32_bf16 v[24:27], v[158:161], v[230:233], v[24:27]
	v_mfma_f32_16x16x32_bf16 v[16:19], v[206:209], v[230:233], v[16:19]
	v_mfma_f32_16x16x32_bf16 v[8:11], v[158:161], v[238:241], v[8:11]
	v_mfma_f32_16x16x32_bf16 v[4:7], v[206:209], v[238:241], v[4:7]
	v_mfma_f32_16x16x32_bf16 v[56:59], v[174:177], v[218:221], v[56:59]
	v_mfma_f32_16x16x32_bf16 v[48:51], v[210:213], v[218:221], v[48:51]
	v_mfma_f32_16x16x32_bf16 v[40:43], v[174:177], v[226:229], v[40:43]
	v_mfma_f32_16x16x32_bf16 v[32:35], v[210:213], v[226:229], v[32:35]
	v_mfma_f32_16x16x32_bf16 v[24:27], v[174:177], v[234:237], v[24:27]
	v_mfma_f32_16x16x32_bf16 v[16:19], v[210:213], v[234:237], v[16:19]
	v_mfma_f32_16x16x32_bf16 v[8:11], v[174:177], v[242:245], v[8:11]
	v_mfma_f32_16x16x32_bf16 v[4:7], v[210:213], v[242:245], v[4:7]
	s_setprio 0
	s_barrier
	s_add_i32 s63, s63, 2
	s_add_u32 s40, s40, 0x100
	s_addc_u32 s41, s41, 0
	s_add_u32 s35, s35, 0x100
	s_addc_u32 s62, s62, 0
	s_cmp_gt_u32 s63, 29
	s_cbranch_scc0 .LBB0_674
	s_and_b64 vcc, exec, s[30:31]
	s_cbranch_vccz .LBB0_677
	s_barrier

; #define PG8_STAGE(bufoff, gbase, voff) do { _Pragma("unroll") for (int _i = 0; _i < 2; ++_i) \
;         __builtin_amdgcn_global_load_lds((const unsigned*)((const char*)(gbase) + (voff)[_i]), (PG8_LAS unsigned*)(lds + (bufoff) + ldsw + _i * 8192), 16, 0, 0); } while (0)
; #define PG8_LDA(dst, b, h) do { _Pragma("unroll") for (int m = 0; m < 4; ++m) _Pragma("unroll") for (int k = 0; k < 2; ++k) dst[m][k] = *(const PG8_LAS bf16x8*)(lds + PG8_SA(b, h) + aoff + m * 2048 + k * 1024); } while (0)
; #define PG8_LDB(dst, b, h) do { _Pragma("unroll") for (int n = 0; n < 2; ++n) _Pragma("unroll") for (int k = 0; k < 2; ++k) dst[n][k] = *(const PG8_LAS bf16x8*)(lds + PG8_SB(b, h) + boff + n * 2048 + k * 1024); } while (0)
; #define PG8_MMA(ai, bj, At, Bt) do { __builtin_amdgcn_s_setprio(1); _Pragma("unroll") for (int m = 0; m < 4; ++m) _Pragma("unroll") for (int n = 0; n < 2; ++n) _Pragma("unroll") for (int k = 0; k < 2; ++k) \
;         acc[ai][bj][m][n] = __builtin_amdgcn_mfma_f32_16x16x32_bf16(Bt[n][k], At[m][k], acc[ai][bj][m][n], 0, 0, 0); __builtin_amdgcn_s_setprio(0); } while (0)
; #define PG8_WAIT_V(n) asm volatile("s_waitcnt vmcnt(" #n ")" ::: "memory")
; #define PG8_WAIT_L(n) asm volatile("s_waitcnt lgkmcnt(" #n ")" ::: "memory")
; template <class Epi, class Sched, bool ALIGN_EPI = false, bool SP2 = false>
; __device__ __forceinline__ void gemm_phase(PG8_LAS unsigned char* lds, const Gemm g, const Sched& S, const Epi& E) {
;     ...
;             const bool last = (t == nt - 2);
;             const char* a1 = cA + (size_t)(t + 1) * kstep;
;             const char* a2 = last ? nA : cA + (size_t)(t + 2) * kstep; const char* b2 = last ? nB : cB + (size_t)(t + 2) * kstep;
;             const char* a3 = a2 + kstep; const char* b3 = b2 + kstep;
;             if (last && has_next) S.a_ready(nxt);
;             if constexpr (SP2) {
;             PG8_LDB(B0, 0, 0); PG8_LDB(B1, 0, 1); PG8_SCHED; PG8_LDA(At, 0, 0); PG8_STAGE(PG8_SA(1, 1), a1 + hstep, voffA);
;             PG8_WAIT_V(8); PG8_WAIT_L(0); PG8_BAR; PG8_MMA(0, 0, At, B0); PG8_MMA(0, 1, At, B1); PG8_BAR; PG8_SCHED;
;             PG8_LDA(At, 0, 1); PG8_STAGE(PG8_SB(0, 0), b2, voffB); PG8_STAGE(PG8_SB(0, 1), b2 + hstep, voffB); PG8_STAGE(PG8_SA(0, 0), a2, voffA);
;             PG8_WAIT_V(8); PG8_WAIT_L(0); PG8_BAR; PG8_MMA(1, 0, At, B0); PG8_MMA(1, 1, At, B1); PG8_BAR; PG8_SCHED;
.LBB0_2096:
	s_add_u32 s27, s40, 0xfffc0080
	s_addc_u32 s29, s41, -1
	s_add_i32 s31, 0, 0x10000
	s_cmp_eq_u32 s26, 12
	s_cselect_b32 s45, s1, s29
	s_cselect_b32 s44, s0, s27
	v_add_u32_e32 v2, s31, v173
	s_cselect_b32 s43, s35, s13
	s_cselect_b32 s42, s34, s11
	s_add_i32 s27, 0, 0x14000
	ds_read_b128 v[134:137], v2
	ds_read_b128 v[138:141], v2 offset:1024
	ds_read_b128 v[154:157], v2 offset:2048
	ds_read_b128 v[158:161], v2 offset:3072
	v_add_u32_e32 v2, s27, v173
	ds_read_b128 v[178:181], v2
	ds_read_b128 v[204:207], v2 offset:1024
	ds_read_b128 v[208:211], v2 offset:2048
	ds_read_b128 v[212:215], v2 offset:3072
	s_add_i32 m0, s55, 0xc000
	ds_read_b128 v[216:219], v177
	ds_read_b128 v[220:223], v177 offset:1024
	ds_read_b128 v[224:227], v177 offset:2048
	ds_read_b128 v[228:231], v177 offset:3072
	ds_read_b128 v[232:235], v177 offset:4096
	ds_read_b128 v[236:239], v177 offset:5120
	ds_read_b128 v[240:243], v177 offset:6144
	ds_read_b128 v[244:247], v177 offset:7168
	global_load_lds_dwordx4 v150, s[40:41]
	s_nop 0
	s_waitcnt vmcnt(7)
	s_waitcnt lgkmcnt(0)
	s_barrier
	s_setprio 1
	s_waitcnt lgkmcnt(0)
	v_mfma_f32_16x16x32_bf16 v[130:133], v[134:137], v[216:219], v[130:133]
	v_mfma_f32_16x16x32_bf16 v[126:129], v[154:157], v[216:219], v[126:129]
	v_mfma_f32_16x16x32_bf16 v[122:125], v[134:137], v[224:227], v[122:125]
	s_add_i32 m0, s55, 0xe000
	v_mfma_f32_16x16x32_bf16 v[118:121], v[154:157], v[224:227], v[118:121]
	global_load_lds_dwordx4 v152, s[40:41]
	v_mfma_f32_16x16x32_bf16 v[114:117], v[134:137], v[232:235], v[114:117]
	v_mfma_f32_16x16x32_bf16 v[110:113], v[154:157], v[232:235], v[110:113]
	v_mfma_f32_16x16x32_bf16 v[106:109], v[134:137], v[240:243], v[106:109]
	v_mfma_f32_16x16x32_bf16 v[102:105], v[154:157], v[240:243], v[102:105]
	v_mfma_f32_16x16x32_bf16 v[130:133], v[138:141], v[220:223], v[130:133]
	v_mfma_f32_16x16x32_bf16 v[126:129], v[158:161], v[220:223], v[126:129]
	v_mfma_f32_16x16x32_bf16 v[122:125], v[138:141], v[228:231], v[122:125]
	v_mfma_f32_16x16x32_bf16 v[118:121], v[158:161], v[228:231], v[118:121]
	v_mfma_f32_16x16x32_bf16 v[114:117], v[138:141], v[236:239], v[114:117]
	v_mfma_f32_16x16x32_bf16 v[110:113], v[158:161], v[236:239], v[110:113]
	v_mfma_f32_16x16x32_bf16 v[106:109], v[138:141], v[244:247], v[106:109]
	v_mfma_f32_16x16x32_bf16 v[102:105], v[158:161], v[244:247], v[102:105]
	s_setprio 0
	s_setprio 1
	v_mfma_f32_16x16x32_bf16 v[98:101], v[178:181], v[216:219], v[98:101]
	v_mfma_f32_16x16x32_bf16 v[94:97], v[208:211], v[216:219], v[94:97]
	v_mfma_f32_16x16x32_bf16 v[90:93], v[178:181], v[224:227], v[90:93]
	v_mfma_f32_16x16x32_bf16 v[86:89], v[208:211], v[224:227], v[86:89]
	v_mfma_f32_16x16x32_bf16 v[82:85], v[178:181], v[232:235], v[82:85]
	v_mfma_f32_16x16x32_bf16 v[78:81], v[208:211], v[232:235], v[78:81]
	v_mfma_f32_16x16x32_bf16 v[74:77], v[178:181], v[240:243], v[74:77]
	v_mfma_f32_16x16x32_bf16 v[70:73], v[208:211], v[240:243], v[70:73]
	v_mfma_f32_16x16x32_bf16 v[98:101], v[204:207], v[220:223], v[98:101]
	v_mfma_f32_16x16x32_bf16 v[94:97], v[212:215], v[220:223], v[94:97]
	v_mfma_f32_16x16x32_bf16 v[90:93], v[204:207], v[228:231], v[90:93]
	v_mfma_f32_16x16x32_bf16 v[86:89], v[212:215], v[228:231], v[86:89]
	v_mfma_f32_16x16x32_bf16 v[82:85], v[204:207], v[236:239], v[82:85]
	v_mfma_f32_16x16x32_bf16 v[78:81], v[212:215], v[236:239], v[78:81]
	v_mfma_f32_16x16x32_bf16 v[74:77], v[204:207], v[244:247], v[74:77]
	v_mfma_f32_16x16x32_bf16 v[70:73], v[212:215], v[244:247], v[70:73]
	s_setprio 0
	s_barrier
	s_add_i32 s29, s31, s54
	s_mov_b32 m0, s29
	ds_read_b128 v[216:219], v177 offset:16384
	ds_read_b128 v[220:223], v177 offset:17408
	ds_read_b128 v[224:227], v177 offset:18432
	ds_read_b128 v[228:231], v177 offset:19456
	ds_read_b128 v[232:235], v177 offset:20480
	ds_read_b128 v[236:239], v177 offset:21504
	ds_read_b128 v[240:243], v177 offset:22528
	ds_read_b128 v[244:247], v177 offset:23552
	global_load_lds_dwordx4 v144, s[42:43]
	s_add_i32 m0, s29, 0x2000
	s_add_u32 s64, s42, 0x40000
	s_addc_u32 s65, s43, 0
	s_add_i32 s27, s27, s54
	global_load_lds_dwordx4 v148, s[42:43]
	s_mov_b32 m0, s27
	s_nop 0
	global_load_lds_dwordx4 v144, s[64:65]
	s_add_i32 m0, s27, 0x2000
	s_nop 0
	global_load_lds_dwordx4 v148, s[64:65]
	s_nop 0
	s_nop 0
	s_nop 0
	s_nop 0
	s_nop 0
	s_nop 0
	s_nop 0
	s_waitcnt vmcnt(6)
	s_waitcnt lgkmcnt(0)
	s_barrier
	s_setprio 1
	s_waitcnt lgkmcnt(0)
	v_mfma_f32_16x16x32_bf16 v[66:69], v[134:137], v[216:219], v[66:69]
	v_mfma_f32_16x16x32_bf16 v[62:65], v[154:157], v[216:219], v[62:65]
	v_mfma_f32_16x16x32_bf16 v[58:61], v[134:137], v[224:227], v[58:61]
	s_mov_b32 m0, s55
	v_mfma_f32_16x16x32_bf16 v[54:57], v[154:157], v[224:227], v[54:57]
	global_load_lds_dwordx4 v142, s[44:45]
	v_mfma_f32_16x16x32_bf16 v[50:53], v[134:137], v[232:235], v[50:53]
	v_mfma_f32_16x16x32_bf16 v[46:49], v[154:157], v[232:235], v[46:49]
	v_mfma_f32_16x16x32_bf16 v[42:45], v[134:137], v[240:243], v[42:45]
	v_mfma_f32_16x16x32_bf16 v[38:41], v[154:157], v[240:243], v[38:41]
	v_mfma_f32_16x16x32_bf16 v[66:69], v[138:141], v[220:223], v[66:69]
	v_mfma_f32_16x16x32_bf16 v[62:65], v[158:161], v[220:223], v[62:65]
	v_mfma_f32_16x16x32_bf16 v[58:61], v[138:141], v[228:231], v[58:61]
	s_mov_b32 m0, s56
	v_mfma_f32_16x16x32_bf16 v[54:57], v[158:161], v[228:231], v[54:57]
	global_load_lds_dwordx4 v146, s[44:45]
	v_mfma_f32_16x16x32_bf16 v[50:53], v[138:141], v[236:239], v[50:53]
	v_mfma_f32_16x16x32_bf16 v[46:49], v[158:161], v[236:239], v[46:49]
	v_mfma_f32_16x16x32_bf16 v[42:45], v[138:141], v[244:247], v[42:45]
	v_mfma_f32_16x16x32_bf16 v[38:41], v[158:161], v[244:247], v[38:41]
	s_setprio 0
	s_setprio 1
	v_mfma_f32_16x16x32_bf16 v[34:37], v[178:181], v[216:219], v[34:37]
	v_mfma_f32_16x16x32_bf16 v[30:33], v[208:211], v[216:219], v[30:33]
	v_mfma_f32_16x16x32_bf16 v[26:29], v[178:181], v[224:227], v[26:29]
	v_mfma_f32_16x16x32_bf16 v[22:25], v[208:211], v[224:227], v[22:25]
	v_mfma_f32_16x16x32_bf16 v[18:21], v[178:181], v[232:235], v[18:21]
	v_mfma_f32_16x16x32_bf16 v[14:17], v[208:211], v[232:235], v[14:17]
	v_mfma_f32_16x16x32_bf16 v[10:13], v[178:181], v[240:243], v[10:13]
	v_mfma_f32_16x16x32_bf16 v[4:7], v[208:211], v[240:243], v[6:9]
	v_mfma_f32_16x16x32_bf16 v[34:37], v[204:207], v[220:223], v[34:37]
	v_mfma_f32_16x16x32_bf16 v[30:33], v[212:215], v[220:223], v[30:33]
	v_mfma_f32_16x16x32_bf16 v[26:29], v[204:207], v[228:231], v[26:29]
	v_mfma_f32_16x16x32_bf16 v[22:25], v[212:215], v[228:231], v[22:25]
	v_mfma_f32_16x16x32_bf16 v[18:21], v[204:207], v[236:239], v[18:21]
	v_mfma_f32_16x16x32_bf16 v[14:17], v[212:215], v[236:239], v[14:17]
	v_mfma_f32_16x16x32_bf16 v[10:13], v[204:207], v[244:247], v[10:13]
	v_mfma_f32_16x16x32_bf16 v[4:7], v[212:215], v[244:247], v[4:7]
	s_setprio 0
	s_barrier
; #define PG8_STAGE(bufoff, gbase, voff) do { _Pragma("unroll") for (int _i = 0; _i < 2; ++_i) \
;         __builtin_amdgcn_global_load_lds((const unsigned*)((const char*)(gbase) + (voff)[_i]), (PG8_LAS unsigned*)(lds + (bufoff) + ldsw + _i * 8192), 16, 0, 0); } while (0)
; #define PG8_LDA(dst, b, h) do { _Pragma("unroll") for (int m = 0; m < 4; ++m) _Pragma("unroll") for (int k = 0; k < 2; ++k) dst[m][k] = *(const PG8_LAS bf16x8*)(lds + PG8_SA(b, h) + aoff + m * 2048 + k * 1024); } while (0)
; #define PG8_LDB(dst, b, h) do { _Pragma("unroll") for (int n = 0; n < 2; ++n) _Pragma("unroll") for (int k = 0; k < 2; ++k) dst[n][k] = *(const PG8_LAS bf16x8*)(lds + PG8_SB(b, h) + boff + n * 2048 + k * 1024); } while (0)
; #define PG8_MMA(ai, bj, At, Bt) do { __builtin_amdgcn_s_setprio(1); _Pragma("unroll") for (int m = 0; m < 4; ++m) _Pragma("unroll") for (int n = 0; n < 2; ++n) _Pragma("unroll") for (int k = 0; k < 2; ++k) \
;         acc[ai][bj][m][n] = __builtin_amdgcn_mfma_f32_16x16x32_bf16(Bt[n][k], At[m][k], acc[ai][bj][m][n], 0, 0, 0); __builtin_amdgcn_s_setprio(0); } while (0)
; #define PG8_WAIT_V(n) asm volatile("s_waitcnt vmcnt(" #n ")" ::: "memory")
; #define PG8_WAIT_L(n) asm volatile("s_waitcnt lgkmcnt(" #n ")" ::: "memory")
; #define PG8_BAR __builtin_amdgcn_s_barrier()
; #define PG8_SCHED __builtin_amdgcn_sched_barrier(0)
; template <class Epi, class Sched, bool ALIGN_EPI = false, bool SP2 = false>
; __device__ __forceinline__ void gemm_phase(PG8_LAS unsigned char* lds, const Gemm g, const Sched& S, const Epi& E) {
;     ...
;             PG8_LDB(B0, 1, 0); PG8_LDB(B1, 1, 1); PG8_SCHED; PG8_LDA(At, 1, 0); PG8_STAGE(PG8_SA(0, 1), a2 + hstep, voffA);
;             PG8_WAIT_V(8); PG8_WAIT_L(0); PG8_BAR; PG8_MMA(0, 0, At, B0); PG8_MMA(0, 1, At, B1); PG8_BAR; PG8_SCHED;
;             PG8_LDA(At, 1, 1); PG8_STAGE(PG8_SB(1, 0), b3, voffB); PG8_STAGE(PG8_SB(1, 1), b3 + hstep, voffB); PG8_STAGE(PG8_SA(1, 0), a3, voffA);
;             PG8_WAIT_V(8); PG8_WAIT_L(0); PG8_BAR; PG8_MMA(1, 0, At, B0); PG8_MMA(1, 1, At, B1); PG8_BAR; PG8_SCHED;
	s_add_i32 s27, 0, 0x18000
	v_add_u32_e32 v2, s27, v173
	s_add_i32 s29, 0, 0x1c000
	ds_read_b128 v[134:137], v2
	ds_read_b128 v[138:141], v2 offset:1024
	ds_read_b128 v[154:157], v2 offset:2048
	ds_read_b128 v[158:161], v2 offset:3072
	v_add_u32_e32 v2, s29, v173
	ds_read_b128 v[178:181], v2
	ds_read_b128 v[204:207], v2 offset:1024
	ds_read_b128 v[208:211], v2 offset:2048
	ds_read_b128 v[212:215], v2 offset:3072
	s_add_u32 s100, s44, 0x80
	s_addc_u32 s101, s45, 0
	s_add_u32 s44, s44, 0x40000
	s_addc_u32 s45, s45, 0
	s_mov_b32 m0, s57
	ds_read_b128 v[216:219], v177 offset:32768
	ds_read_b128 v[220:223], v177 offset:33792
	ds_read_b128 v[224:227], v177 offset:34816
	ds_read_b128 v[228:231], v177 offset:35840
	ds_read_b128 v[232:235], v177 offset:36864
	ds_read_b128 v[236:239], v177 offset:37888
	ds_read_b128 v[240:243], v177 offset:38912
	ds_read_b128 v[244:247], v177 offset:39936
	global_load_lds_dwordx4 v142, s[44:45]
	s_waitcnt vmcnt(7)
	s_waitcnt lgkmcnt(0)
	s_barrier
	s_setprio 1
	s_waitcnt lgkmcnt(0)
	v_mfma_f32_16x16x32_bf16 v[130:133], v[134:137], v[216:219], v[130:133]
	v_mfma_f32_16x16x32_bf16 v[126:129], v[154:157], v[216:219], v[126:129]
	v_mfma_f32_16x16x32_bf16 v[122:125], v[134:137], v[224:227], v[122:125]
	s_mov_b32 m0, s58
	v_mfma_f32_16x16x32_bf16 v[118:121], v[154:157], v[224:227], v[118:121]
	global_load_lds_dwordx4 v146, s[44:45]
	v_mfma_f32_16x16x32_bf16 v[114:117], v[134:137], v[232:235], v[114:117]
	v_mfma_f32_16x16x32_bf16 v[110:113], v[154:157], v[232:235], v[110:113]
	v_mfma_f32_16x16x32_bf16 v[106:109], v[134:137], v[240:243], v[106:109]
	v_mfma_f32_16x16x32_bf16 v[102:105], v[154:157], v[240:243], v[102:105]
	v_mfma_f32_16x16x32_bf16 v[130:133], v[138:141], v[220:223], v[130:133]
	v_mfma_f32_16x16x32_bf16 v[126:129], v[158:161], v[220:223], v[126:129]
	v_mfma_f32_16x16x32_bf16 v[122:125], v[138:141], v[228:231], v[122:125]
	v_mfma_f32_16x16x32_bf16 v[118:121], v[158:161], v[228:231], v[118:121]
	v_mfma_f32_16x16x32_bf16 v[114:117], v[138:141], v[236:239], v[114:117]
	v_mfma_f32_16x16x32_bf16 v[110:113], v[158:161], v[236:239], v[110:113]
	v_mfma_f32_16x16x32_bf16 v[106:109], v[138:141], v[244:247], v[106:109]
	v_mfma_f32_16x16x32_bf16 v[102:105], v[158:161], v[244:247], v[102:105]
	s_setprio 0
	s_setprio 1
	v_mfma_f32_16x16x32_bf16 v[98:101], v[178:181], v[216:219], v[98:101]
	v_mfma_f32_16x16x32_bf16 v[94:97], v[208:211], v[216:219], v[94:97]
	v_mfma_f32_16x16x32_bf16 v[90:93], v[178:181], v[224:227], v[90:93]
	v_mfma_f32_16x16x32_bf16 v[86:89], v[208:211], v[224:227], v[86:89]
	v_mfma_f32_16x16x32_bf16 v[82:85], v[178:181], v[232:235], v[82:85]
	v_mfma_f32_16x16x32_bf16 v[78:81], v[208:211], v[232:235], v[78:81]
	v_mfma_f32_16x16x32_bf16 v[74:77], v[178:181], v[240:243], v[74:77]
	v_mfma_f32_16x16x32_bf16 v[70:73], v[208:211], v[240:243], v[70:73]
	v_mfma_f32_16x16x32_bf16 v[98:101], v[204:207], v[220:223], v[98:101]
	v_mfma_f32_16x16x32_bf16 v[94:97], v[212:215], v[220:223], v[94:97]
	v_mfma_f32_16x16x32_bf16 v[90:93], v[204:207], v[228:231], v[90:93]
	v_mfma_f32_16x16x32_bf16 v[86:89], v[212:215], v[228:231], v[86:89]
	v_mfma_f32_16x16x32_bf16 v[82:85], v[204:207], v[236:239], v[82:85]
	v_mfma_f32_16x16x32_bf16 v[78:81], v[212:215], v[236:239], v[78:81]
	v_mfma_f32_16x16x32_bf16 v[74:77], v[204:207], v[244:247], v[74:77]
	v_mfma_f32_16x16x32_bf16 v[70:73], v[212:215], v[244:247], v[70:73]
	s_setprio 0
	s_barrier
	s_add_i32 s27, s27, s54
	s_add_i32 m0, s27, 0xffffff80
	ds_read_b128 v[216:219], v177 offset:49152
	ds_read_b128 v[220:223], v177 offset:50176
	ds_read_b128 v[224:227], v177 offset:51200
	ds_read_b128 v[228:231], v177 offset:52224
	ds_read_b128 v[232:235], v177 offset:53248
	ds_read_b128 v[236:239], v177 offset:54272
	ds_read_b128 v[240:243], v177 offset:55296
	ds_read_b128 v[244:247], v177 offset:56320
	global_load_lds_dwordx4 v144, s[42:43] offset:128
	s_add_i32 m0, s27, 0x1f80
	s_add_i32 s27, s29, s54
	global_load_lds_dwordx4 v148, s[42:43] offset:128
	s_add_u32 s42, s42, 0x40080
	s_addc_u32 s43, s43, 0
	s_mov_b32 m0, s27
	s_nop 0
	global_load_lds_dwordx4 v144, s[42:43]
	s_add_i32 m0, s27, 0x2000
	s_nop 0
	global_load_lds_dwordx4 v148, s[42:43]
	s_waitcnt vmcnt(6)
	s_waitcnt lgkmcnt(0)
	s_barrier
	s_setprio 1
	s_waitcnt lgkmcnt(0)
	v_mfma_f32_16x16x32_bf16 v[66:69], v[134:137], v[216:219], v[66:69]
	v_mfma_f32_16x16x32_bf16 v[62:65], v[154:157], v[216:219], v[62:65]
	v_mfma_f32_16x16x32_bf16 v[58:61], v[134:137], v[224:227], v[58:61]
	s_mov_b32 m0, s61
	v_mfma_f32_16x16x32_bf16 v[54:57], v[154:157], v[224:227], v[54:57]
	global_load_lds_dwordx4 v142, s[100:101]
	v_mfma_f32_16x16x32_bf16 v[50:53], v[134:137], v[232:235], v[50:53]
	v_mfma_f32_16x16x32_bf16 v[46:49], v[154:157], v[232:235], v[46:49]
	v_mfma_f32_16x16x32_bf16 v[42:45], v[134:137], v[240:243], v[42:45]
	v_mfma_f32_16x16x32_bf16 v[38:41], v[154:157], v[240:243], v[38:41]
	v_mfma_f32_16x16x32_bf16 v[66:69], v[138:141], v[220:223], v[66:69]
	v_mfma_f32_16x16x32_bf16 v[62:65], v[158:161], v[220:223], v[62:65]
	v_mfma_f32_16x16x32_bf16 v[58:61], v[138:141], v[228:231], v[58:61]
	s_mov_b32 m0, s62
	v_mfma_f32_16x16x32_bf16 v[54:57], v[158:161], v[228:231], v[54:57]
	global_load_lds_dwordx4 v146, s[100:101]
	v_mfma_f32_16x16x32_bf16 v[50:53], v[138:141], v[236:239], v[50:53]
	v_mfma_f32_16x16x32_bf16 v[46:49], v[158:161], v[236:239], v[46:49]
	v_mfma_f32_16x16x32_bf16 v[42:45], v[138:141], v[244:247], v[42:45]
	v_mfma_f32_16x16x32_bf16 v[38:41], v[158:161], v[244:247], v[38:41]
	s_setprio 0
	s_setprio 1
	v_mfma_f32_16x16x32_bf16 v[34:37], v[178:181], v[216:219], v[34:37]
	v_mfma_f32_16x16x32_bf16 v[30:33], v[208:211], v[216:219], v[30:33]
	v_mfma_f32_16x16x32_bf16 v[26:29], v[178:181], v[224:227], v[26:29]
	v_mfma_f32_16x16x32_bf16 v[22:25], v[208:211], v[224:227], v[22:25]
	v_mfma_f32_16x16x32_bf16 v[18:21], v[178:181], v[232:235], v[18:21]
	v_mfma_f32_16x16x32_bf16 v[14:17], v[208:211], v[232:235], v[14:17]
	v_mfma_f32_16x16x32_bf16 v[8:11], v[178:181], v[240:243], v[10:13]
	v_mfma_f32_16x16x32_bf16 v[4:7], v[208:211], v[240:243], v[4:7]
	v_mfma_f32_16x16x32_bf16 v[34:37], v[204:207], v[220:223], v[34:37]
	v_mfma_f32_16x16x32_bf16 v[30:33], v[212:215], v[220:223], v[30:33]
	v_mfma_f32_16x16x32_bf16 v[26:29], v[204:207], v[228:231], v[26:29]
	v_mfma_f32_16x16x32_bf16 v[22:25], v[212:215], v[228:231], v[22:25]
	v_mfma_f32_16x16x32_bf16 v[18:21], v[204:207], v[236:239], v[18:21]
	v_mfma_f32_16x16x32_bf16 v[14:17], v[212:215], v[236:239], v[14:17]
	v_mfma_f32_16x16x32_bf16 v[10:13], v[204:207], v[244:247], v[8:11]
	v_mfma_f32_16x16x32_bf16 v[6:9], v[212:215], v[244:247], v[4:7]
	s_setprio 0
	s_barrier
	s_add_i32 s26, s26, 2
	s_add_u32 s40, s40, 0x100
	s_addc_u32 s41, s41, 0
	s_add_u32 s11, s11, 0x100
	s_addc_u32 s13, s13, 0
	s_cmp_gt_u32 s26, 13
	s_cbranch_scc0 .LBB0_2096
	s_and_b64 vcc, exec, s[8:9]
	s_cbranch_vccz .LBB0_2099
	s_barrier

; #define PG8_STAGE(bufoff, gbase, voff) do { _Pragma("unroll") for (int _i = 0; _i < 2; ++_i) \
;         __builtin_amdgcn_global_load_lds((const unsigned*)((const char*)(gbase) + (voff)[_i]), (PG8_LAS unsigned*)(lds + (bufoff) + ldsw + _i * 8192), 16, 0, 0); } while (0)
; #define PG8_LDA(dst, b, h) do { _Pragma("unroll") for (int m = 0; m < 4; ++m) _Pragma("unroll") for (int k = 0; k < 2; ++k) dst[m][k] = *(const PG8_LAS bf16x8*)(lds + PG8_SA(b, h) + aoff + m * 2048 + k * 1024); } while (0)
; #define PG8_LDB(dst, b, h) do { _Pragma("unroll") for (int n = 0; n < 2; ++n) _Pragma("unroll") for (int k = 0; k < 2; ++k) dst[n][k] = *(const PG8_LAS bf16x8*)(lds + PG8_SB(b, h) + boff + n * 2048 + k * 1024); } while (0)
; #define PG8_MMA(ai, bj, At, Bt) do { __builtin_amdgcn_s_setprio(1); _Pragma("unroll") for (int m = 0; m < 4; ++m) _Pragma("unroll") for (int n = 0; n < 2; ++n) _Pragma("unroll") for (int k = 0; k < 2; ++k) \
;         acc[ai][bj][m][n] = __builtin_amdgcn_mfma_f32_16x16x32_bf16(Bt[n][k], At[m][k], acc[ai][bj][m][n], 0, 0, 0); __builtin_amdgcn_s_setprio(0); } while (0)
; #define PG8_WAIT_V(n) asm volatile("s_waitcnt vmcnt(" #n ")" ::: "memory")
; #define PG8_WAIT_L(n) asm volatile("s_waitcnt lgkmcnt(" #n ")" ::: "memory")
; #define PG8_BAR __builtin_amdgcn_s_barrier()
; #define PG8_SCHED __builtin_amdgcn_sched_barrier(0)
; template <class Epi, class Sched, bool ALIGN_EPI = false, bool SP2 = false>
; __device__ __forceinline__ void gemm_phase(PG8_LAS unsigned char* lds, const Gemm g, const Sched& S, const Epi& E) {
;     ...
;         for (int t = 0; t < nt; t += 2) {
;             const bool last = (t == nt - 2);
;             const char* a1 = cA + (size_t)(t + 1) * kstep;
;             const char* a2 = last ? nA : cA + (size_t)(t + 2) * kstep; const char* b2 = last ? nB : cB + (size_t)(t + 2) * kstep;
;             const char* a3 = a2 + kstep; const char* b3 = b2 + kstep;
;             if (last && has_next) S.a_ready(nxt);
;             if constexpr (SP2) {
;             PG8_LDB(B0, 0, 0); PG8_LDB(B1, 0, 1); PG8_SCHED; PG8_LDA(At, 0, 0); PG8_STAGE(PG8_SA(1, 1), a1 + hstep, voffA);
;             PG8_WAIT_V(8); PG8_WAIT_L(0); PG8_BAR; PG8_MMA(0, 0, At, B0); PG8_MMA(0, 1, At, B1); PG8_BAR; PG8_SCHED;
;             PG8_LDA(At, 0, 1); PG8_STAGE(PG8_SB(0, 0), b2, voffB); PG8_STAGE(PG8_SB(0, 1), b2 + hstep, voffB); PG8_STAGE(PG8_SA(0, 0), a2, voffA);
.LBB0_2185:
	s_add_u32 s42, s40, 0x100
	s_addc_u32 s43, s41, 0
	s_add_i32 s37, 0, 0x10000
	s_cmp_eq_u32 s31, 28
	s_cselect_b32 s47, s5, s43
	s_cselect_b32 s46, s4, s42
	v_add_u32_e32 v135, s37, v173
	s_cselect_b32 s45, s35, s29
	s_cselect_b32 s44, s34, s2
	s_add_i32 s39, 0, 0x14000
	ds_read_b128 v[142:145], v135
	ds_read_b128 v[146:149], v135 offset:1024
	ds_read_b128 v[150:153], v135 offset:2048
	ds_read_b128 v[154:157], v135 offset:3072
	v_add_u32_e32 v135, s39, v173
	ds_read_b128 v[158:161], v135
	ds_read_b128 v[174:177], v135 offset:1024
	ds_read_b128 v[180:183], v135 offset:2048
	ds_read_b128 v[204:207], v135 offset:3072
	v_lshl_add_u64 v[162:163], s[40:41], 0, v[138:139]
	s_add_i32 m0, s55, 0xc000
	ds_read_b128 v[208:211], v179
	ds_read_b128 v[212:215], v179 offset:1024
	ds_read_b128 v[216:219], v179 offset:2048
	ds_read_b128 v[220:223], v179 offset:3072
	ds_read_b128 v[224:227], v179 offset:4096
	ds_read_b128 v[228:231], v179 offset:5120
	ds_read_b128 v[232:235], v179 offset:6144
	ds_read_b128 v[236:239], v179 offset:7168
	global_load_lds_dwordx4 v[162:163], off
	v_lshl_add_u64 v[162:163], s[40:41], 0, v[140:141]
	s_nop 0
	s_waitcnt vmcnt(7)
	s_waitcnt lgkmcnt(0)
	s_barrier
	s_setprio 1
	s_waitcnt lgkmcnt(0)
	v_mfma_f32_16x16x32_bf16 v[128:131], v[142:145], v[208:211], v[128:131]
	v_mfma_f32_16x16x32_bf16 v[124:127], v[150:153], v[208:211], v[124:127]
	v_mfma_f32_16x16x32_bf16 v[112:115], v[142:145], v[216:219], v[112:115]
	s_add_i32 m0, s55, 0xe000
	v_mfma_f32_16x16x32_bf16 v[108:111], v[150:153], v[216:219], v[108:111]
	global_load_lds_dwordx4 v[162:163], off
	v_mfma_f32_16x16x32_bf16 v[96:99], v[142:145], v[224:227], v[96:99]
	v_mfma_f32_16x16x32_bf16 v[92:95], v[150:153], v[224:227], v[92:95]
	v_mfma_f32_16x16x32_bf16 v[80:83], v[142:145], v[232:235], v[80:83]
	v_mfma_f32_16x16x32_bf16 v[76:79], v[150:153], v[232:235], v[76:79]
	v_mfma_f32_16x16x32_bf16 v[128:131], v[146:149], v[212:215], v[128:131]
	v_mfma_f32_16x16x32_bf16 v[124:127], v[154:157], v[212:215], v[124:127]
	v_mfma_f32_16x16x32_bf16 v[112:115], v[146:149], v[220:223], v[112:115]
	v_mfma_f32_16x16x32_bf16 v[108:111], v[154:157], v[220:223], v[108:111]
	v_mfma_f32_16x16x32_bf16 v[96:99], v[146:149], v[228:231], v[96:99]
	v_mfma_f32_16x16x32_bf16 v[92:95], v[154:157], v[228:231], v[92:95]
	v_mfma_f32_16x16x32_bf16 v[80:83], v[146:149], v[236:239], v[80:83]
	v_mfma_f32_16x16x32_bf16 v[76:79], v[154:157], v[236:239], v[76:79]
	s_setprio 0
	s_setprio 1
	v_mfma_f32_16x16x32_bf16 v[120:123], v[158:161], v[208:211], v[120:123]
	v_mfma_f32_16x16x32_bf16 v[116:119], v[180:183], v[208:211], v[116:119]
	v_mfma_f32_16x16x32_bf16 v[104:107], v[158:161], v[216:219], v[104:107]
	v_mfma_f32_16x16x32_bf16 v[100:103], v[180:183], v[216:219], v[100:103]
	v_mfma_f32_16x16x32_bf16 v[88:91], v[158:161], v[224:227], v[88:91]
	v_mfma_f32_16x16x32_bf16 v[84:87], v[180:183], v[224:227], v[84:87]
	v_mfma_f32_16x16x32_bf16 v[72:75], v[158:161], v[232:235], v[72:75]
	v_mfma_f32_16x16x32_bf16 v[68:71], v[180:183], v[232:235], v[68:71]
	v_mfma_f32_16x16x32_bf16 v[120:123], v[174:177], v[212:215], v[120:123]
	v_mfma_f32_16x16x32_bf16 v[116:119], v[204:207], v[212:215], v[116:119]
	v_mfma_f32_16x16x32_bf16 v[104:107], v[174:177], v[220:223], v[104:107]
	v_mfma_f32_16x16x32_bf16 v[100:103], v[204:207], v[220:223], v[100:103]
	v_mfma_f32_16x16x32_bf16 v[88:91], v[174:177], v[228:231], v[88:91]
	v_mfma_f32_16x16x32_bf16 v[84:87], v[204:207], v[228:231], v[84:87]
	v_mfma_f32_16x16x32_bf16 v[72:75], v[174:177], v[236:239], v[72:75]
	v_mfma_f32_16x16x32_bf16 v[68:71], v[204:207], v[236:239], v[68:71]
	s_setprio 0
	s_barrier
	s_add_i32 s37, s37, s54
	s_mov_b32 m0, s37
	ds_read_b128 v[208:211], v179 offset:16384
	ds_read_b128 v[212:215], v179 offset:17408
	ds_read_b128 v[216:219], v179 offset:18432
	ds_read_b128 v[220:223], v179 offset:19456
	ds_read_b128 v[224:227], v179 offset:20480
	ds_read_b128 v[228:231], v179 offset:21504
	ds_read_b128 v[232:235], v179 offset:22528
	ds_read_b128 v[236:239], v179 offset:23552
	global_load_lds_dwordx4 v2, s[44:45]
	s_add_i32 m0, s37, 0x2000
	s_add_u32 s40, s44, 0x80000
	s_addc_u32 s41, s45, 0
	s_add_i32 s37, s39, s54
	global_load_lds_dwordx4 v132, s[44:45]
	s_mov_b32 m0, s37
	s_nop 0
	global_load_lds_dwordx4 v2, s[40:41]
	s_add_i32 m0, s37, 0x2000
	s_nop 0
	global_load_lds_dwordx4 v132, s[40:41]
	s_nop 0
	s_nop 0
	s_nop 0
	s_nop 0
	s_nop 0
	s_nop 0
	s_nop 0
	s_waitcnt vmcnt(6)
	s_waitcnt lgkmcnt(0)
	s_barrier
; #define PG8_STAGE(bufoff, gbase, voff) do { _Pragma("unroll") for (int _i = 0; _i < 2; ++_i) \
;         __builtin_amdgcn_global_load_lds((const unsigned*)((const char*)(gbase) + (voff)[_i]), (PG8_LAS unsigned*)(lds + (bufoff) + ldsw + _i * 8192), 16, 0, 0); } while (0)
; #define PG8_LDA(dst, b, h) do { _Pragma("unroll") for (int m = 0; m < 4; ++m) _Pragma("unroll") for (int k = 0; k < 2; ++k) dst[m][k] = *(const PG8_LAS bf16x8*)(lds + PG8_SA(b, h) + aoff + m * 2048 + k * 1024); } while (0)
; #define PG8_LDB(dst, b, h) do { _Pragma("unroll") for (int n = 0; n < 2; ++n) _Pragma("unroll") for (int k = 0; k < 2; ++k) dst[n][k] = *(const PG8_LAS bf16x8*)(lds + PG8_SB(b, h) + boff + n * 2048 + k * 1024); } while (0)
; #define PG8_MMA(ai, bj, At, Bt) do { __builtin_amdgcn_s_setprio(1); _Pragma("unroll") for (int m = 0; m < 4; ++m) _Pragma("unroll") for (int n = 0; n < 2; ++n) _Pragma("unroll") for (int k = 0; k < 2; ++k) \
;         acc[ai][bj][m][n] = __builtin_amdgcn_mfma_f32_16x16x32_bf16(Bt[n][k], At[m][k], acc[ai][bj][m][n], 0, 0, 0); __builtin_amdgcn_s_setprio(0); } while (0)
; #define PG8_WAIT_V(n) asm volatile("s_waitcnt vmcnt(" #n ")" ::: "memory")
; #define PG8_WAIT_L(n) asm volatile("s_waitcnt lgkmcnt(" #n ")" ::: "memory")
; #define PG8_BAR __builtin_amdgcn_s_barrier()
; #define PG8_SCHED __builtin_amdgcn_sched_barrier(0)
; template <class Epi, class Sched, bool ALIGN_EPI = false, bool SP2 = false>
; __device__ __forceinline__ void gemm_phase(PG8_LAS unsigned char* lds, const Gemm g, const Sched& S, const Epi& E) {
;     ...
;             PG8_LDA(At, 0, 1); PG8_STAGE(PG8_SB(0, 0), b2, voffB); PG8_STAGE(PG8_SB(0, 1), b2 + hstep, voffB); PG8_STAGE(PG8_SA(0, 0), a2, voffA);
;             PG8_WAIT_V(8); PG8_WAIT_L(0); PG8_BAR; PG8_MMA(1, 0, At, B0); PG8_MMA(1, 1, At, B1); PG8_BAR; PG8_SCHED;
;             PG8_LDB(B0, 1, 0); PG8_LDB(B1, 1, 1); PG8_SCHED; PG8_LDA(At, 1, 0); PG8_STAGE(PG8_SA(0, 1), a2 + hstep, voffA);
;             PG8_WAIT_V(8); PG8_WAIT_L(0); PG8_BAR; PG8_MMA(0, 0, At, B0); PG8_MMA(0, 1, At, B1); PG8_BAR; PG8_SCHED;
	s_setprio 1
	s_waitcnt lgkmcnt(0)
	v_mfma_f32_16x16x32_bf16 v[64:67], v[142:145], v[208:211], v[64:67]
	v_mfma_f32_16x16x32_bf16 v[60:63], v[150:153], v[208:211], v[60:63]
	v_mfma_f32_16x16x32_bf16 v[48:51], v[142:145], v[216:219], v[48:51]
	s_mov_b32 m0, s55
	v_mfma_f32_16x16x32_bf16 v[44:47], v[150:153], v[216:219], v[44:47]
	global_load_lds_dwordx4 v2, s[46:47]
	v_mfma_f32_16x16x32_bf16 v[32:35], v[142:145], v[224:227], v[32:35]
	v_mfma_f32_16x16x32_bf16 v[28:31], v[150:153], v[224:227], v[28:31]
	v_mfma_f32_16x16x32_bf16 v[16:19], v[142:145], v[232:235], v[16:19]
	v_mfma_f32_16x16x32_bf16 v[12:15], v[150:153], v[232:235], v[12:15]
	v_mfma_f32_16x16x32_bf16 v[64:67], v[146:149], v[212:215], v[64:67]
	v_mfma_f32_16x16x32_bf16 v[60:63], v[154:157], v[212:215], v[60:63]
	v_mfma_f32_16x16x32_bf16 v[48:51], v[146:149], v[220:223], v[48:51]
	s_mov_b32 m0, s56
	v_mfma_f32_16x16x32_bf16 v[44:47], v[154:157], v[220:223], v[44:47]
	global_load_lds_dwordx4 v132, s[46:47]
	v_mfma_f32_16x16x32_bf16 v[32:35], v[146:149], v[228:231], v[32:35]
	v_mfma_f32_16x16x32_bf16 v[28:31], v[154:157], v[228:231], v[28:31]
	v_mfma_f32_16x16x32_bf16 v[16:19], v[146:149], v[236:239], v[16:19]
	v_mfma_f32_16x16x32_bf16 v[12:15], v[154:157], v[236:239], v[12:15]
	s_setprio 0
	s_setprio 1
	v_mfma_f32_16x16x32_bf16 v[56:59], v[158:161], v[208:211], v[56:59]
	v_mfma_f32_16x16x32_bf16 v[52:55], v[180:183], v[208:211], v[52:55]
	v_mfma_f32_16x16x32_bf16 v[40:43], v[158:161], v[216:219], v[40:43]
	v_mfma_f32_16x16x32_bf16 v[36:39], v[180:183], v[216:219], v[36:39]
	v_mfma_f32_16x16x32_bf16 v[24:27], v[158:161], v[224:227], v[24:27]
	v_mfma_f32_16x16x32_bf16 v[20:23], v[180:183], v[224:227], v[20:23]
	v_mfma_f32_16x16x32_bf16 v[8:11], v[158:161], v[232:235], v[8:11]
	v_mfma_f32_16x16x32_bf16 v[4:7], v[180:183], v[232:235], v[4:7]
	v_mfma_f32_16x16x32_bf16 v[56:59], v[174:177], v[212:215], v[56:59]
	v_mfma_f32_16x16x32_bf16 v[52:55], v[204:207], v[212:215], v[52:55]
	v_mfma_f32_16x16x32_bf16 v[40:43], v[174:177], v[220:223], v[40:43]
	v_mfma_f32_16x16x32_bf16 v[36:39], v[204:207], v[220:223], v[36:39]
	v_mfma_f32_16x16x32_bf16 v[24:27], v[174:177], v[228:231], v[24:27]
	v_mfma_f32_16x16x32_bf16 v[20:23], v[204:207], v[228:231], v[20:23]
	v_mfma_f32_16x16x32_bf16 v[8:11], v[174:177], v[236:239], v[8:11]
	v_mfma_f32_16x16x32_bf16 v[4:7], v[204:207], v[236:239], v[4:7]
	s_setprio 0
	s_barrier
	s_add_i32 s37, 0, 0x18000
	v_add_u32_e32 v135, s37, v173
	s_add_i32 s39, 0, 0x1c000
	ds_read_b128 v[142:145], v135
	ds_read_b128 v[146:149], v135 offset:1024
	ds_read_b128 v[150:153], v135 offset:2048
	ds_read_b128 v[154:157], v135 offset:3072
	v_add_u32_e32 v135, s39, v173
	ds_read_b128 v[158:161], v135
	ds_read_b128 v[174:177], v135 offset:1024
	ds_read_b128 v[180:183], v135 offset:2048
	ds_read_b128 v[204:207], v135 offset:3072
	s_add_u32 s40, s46, 0x80000
	s_addc_u32 s41, s47, 0
	s_mov_b32 m0, s57
	ds_read_b128 v[208:211], v179 offset:32768
	ds_read_b128 v[212:215], v179 offset:33792
	ds_read_b128 v[216:219], v179 offset:34816
	ds_read_b128 v[220:223], v179 offset:35840
	ds_read_b128 v[224:227], v179 offset:36864
	ds_read_b128 v[228:231], v179 offset:37888
	ds_read_b128 v[232:235], v179 offset:38912
	ds_read_b128 v[236:239], v179 offset:39936
	global_load_lds_dwordx4 v2, s[40:41]
	s_waitcnt vmcnt(7)
	s_waitcnt lgkmcnt(0)
	s_barrier
	s_setprio 1
	s_waitcnt lgkmcnt(0)
	v_mfma_f32_16x16x32_bf16 v[128:131], v[142:145], v[208:211], v[128:131]
	v_mfma_f32_16x16x32_bf16 v[124:127], v[150:153], v[208:211], v[124:127]
	v_mfma_f32_16x16x32_bf16 v[112:115], v[142:145], v[216:219], v[112:115]
	s_mov_b32 m0, s58
	v_mfma_f32_16x16x32_bf16 v[108:111], v[150:153], v[216:219], v[108:111]
	global_load_lds_dwordx4 v132, s[40:41]
	v_mfma_f32_16x16x32_bf16 v[96:99], v[142:145], v[224:227], v[96:99]
	v_mfma_f32_16x16x32_bf16 v[92:95], v[150:153], v[224:227], v[92:95]
	v_mfma_f32_16x16x32_bf16 v[80:83], v[142:145], v[232:235], v[80:83]
	v_mfma_f32_16x16x32_bf16 v[76:79], v[150:153], v[232:235], v[76:79]
	v_mfma_f32_16x16x32_bf16 v[128:131], v[146:149], v[212:215], v[128:131]
	v_mfma_f32_16x16x32_bf16 v[124:127], v[154:157], v[212:215], v[124:127]
	v_mfma_f32_16x16x32_bf16 v[112:115], v[146:149], v[220:223], v[112:115]
	v_mfma_f32_16x16x32_bf16 v[108:111], v[154:157], v[220:223], v[108:111]
	v_mfma_f32_16x16x32_bf16 v[96:99], v[146:149], v[228:231], v[96:99]
	v_mfma_f32_16x16x32_bf16 v[92:95], v[154:157], v[228:231], v[92:95]
	v_mfma_f32_16x16x32_bf16 v[80:83], v[146:149], v[236:239], v[80:83]
	v_mfma_f32_16x16x32_bf16 v[76:79], v[154:157], v[236:239], v[76:79]
	s_setprio 0
	s_setprio 1
	v_mfma_f32_16x16x32_bf16 v[120:123], v[158:161], v[208:211], v[120:123]
	v_mfma_f32_16x16x32_bf16 v[116:119], v[180:183], v[208:211], v[116:119]
	v_mfma_f32_16x16x32_bf16 v[104:107], v[158:161], v[216:219], v[104:107]
	v_mfma_f32_16x16x32_bf16 v[100:103], v[180:183], v[216:219], v[100:103]
	v_mfma_f32_16x16x32_bf16 v[88:91], v[158:161], v[224:227], v[88:91]
	v_mfma_f32_16x16x32_bf16 v[84:87], v[180:183], v[224:227], v[84:87]
	v_mfma_f32_16x16x32_bf16 v[72:75], v[158:161], v[232:235], v[72:75]
	v_mfma_f32_16x16x32_bf16 v[68:71], v[180:183], v[232:235], v[68:71]
	v_mfma_f32_16x16x32_bf16 v[120:123], v[174:177], v[212:215], v[120:123]
	v_mfma_f32_16x16x32_bf16 v[116:119], v[204:207], v[212:215], v[116:119]
	v_mfma_f32_16x16x32_bf16 v[104:107], v[174:177], v[220:223], v[104:107]
	v_mfma_f32_16x16x32_bf16 v[100:103], v[204:207], v[220:223], v[100:103]
	v_mfma_f32_16x16x32_bf16 v[88:91], v[174:177], v[228:231], v[88:91]
	v_mfma_f32_16x16x32_bf16 v[84:87], v[204:207], v[228:231], v[84:87]
	v_mfma_f32_16x16x32_bf16 v[72:75], v[174:177], v[236:239], v[72:75]
	v_mfma_f32_16x16x32_bf16 v[68:71], v[204:207], v[236:239], v[68:71]
	s_setprio 0
	s_barrier
; #define PG8_STAGE(bufoff, gbase, voff) do { _Pragma("unroll") for (int _i = 0; _i < 2; ++_i) \
;         __builtin_amdgcn_global_load_lds((const unsigned*)((const char*)(gbase) + (voff)[_i]), (PG8_LAS unsigned*)(lds + (bufoff) + ldsw + _i * 8192), 16, 0, 0); } while (0)
; #define PG8_LDA(dst, b, h) do { _Pragma("unroll") for (int m = 0; m < 4; ++m) _Pragma("unroll") for (int k = 0; k < 2; ++k) dst[m][k] = *(const PG8_LAS bf16x8*)(lds + PG8_SA(b, h) + aoff + m * 2048 + k * 1024); } while (0)
; #define PG8_MMA(ai, bj, At, Bt) do { __builtin_amdgcn_s_setprio(1); _Pragma("unroll") for (int m = 0; m < 4; ++m) _Pragma("unroll") for (int n = 0; n < 2; ++n) _Pragma("unroll") for (int k = 0; k < 2; ++k) \
;         acc[ai][bj][m][n] = __builtin_amdgcn_mfma_f32_16x16x32_bf16(Bt[n][k], At[m][k], acc[ai][bj][m][n], 0, 0, 0); __builtin_amdgcn_s_setprio(0); } while (0)
; #define PG8_WAIT_V(n) asm volatile("s_waitcnt vmcnt(" #n ")" ::: "memory")
; #define PG8_WAIT_L(n) asm volatile("s_waitcnt lgkmcnt(" #n ")" ::: "memory")
; #define PG8_BAR __builtin_amdgcn_s_barrier()
; #define PG8_SCHED __builtin_amdgcn_sched_barrier(0)
; template <class Epi, class Sched, bool ALIGN_EPI = false, bool SP2 = false>
; __device__ __forceinline__ void gemm_phase(PG8_LAS unsigned char* lds, const Gemm g, const Sched& S, const Epi& E) {
;     ...
;             PG8_LDA(At, 1, 1); PG8_STAGE(PG8_SB(1, 0), b3, voffB); PG8_STAGE(PG8_SB(1, 1), b3 + hstep, voffB); PG8_STAGE(PG8_SA(1, 0), a3, voffA);
;             PG8_WAIT_V(8); PG8_WAIT_L(0); PG8_BAR; PG8_MMA(1, 0, At, B0); PG8_MMA(1, 1, At, B1); PG8_BAR; PG8_SCHED;
	s_add_i32 s37, s37, s54
	s_add_i32 m0, s37, 0xffffff80
	ds_read_b128 v[208:211], v179 offset:49152
	ds_read_b128 v[212:215], v179 offset:50176
	ds_read_b128 v[216:219], v179 offset:51200
	ds_read_b128 v[220:223], v179 offset:52224
	ds_read_b128 v[224:227], v179 offset:53248
	ds_read_b128 v[228:231], v179 offset:54272
	ds_read_b128 v[232:235], v179 offset:55296
	ds_read_b128 v[236:239], v179 offset:56320
	global_load_lds_dwordx4 v2, s[44:45] offset:128
	s_add_i32 m0, s37, 0x1f80
	s_add_u32 s40, s44, 0x80080
	s_addc_u32 s41, s45, 0
	s_add_i32 s37, s39, s54
	global_load_lds_dwordx4 v132, s[44:45] offset:128
	s_mov_b32 m0, s37
	s_nop 0
	global_load_lds_dwordx4 v2, s[40:41]
	s_add_i32 m0, s37, 0x2000
	s_nop 0
	global_load_lds_dwordx4 v132, s[40:41]
	s_waitcnt vmcnt(6)
	s_waitcnt lgkmcnt(0)
	s_barrier
	s_setprio 1
	s_waitcnt lgkmcnt(0)
	v_mfma_f32_16x16x32_bf16 v[64:67], v[142:145], v[208:211], v[64:67]
	v_mfma_f32_16x16x32_bf16 v[60:63], v[150:153], v[208:211], v[60:63]
	v_mfma_f32_16x16x32_bf16 v[48:51], v[142:145], v[216:219], v[48:51]
	s_add_i32 m0, s60, 0xffffff80
	v_mfma_f32_16x16x32_bf16 v[44:47], v[150:153], v[216:219], v[44:47]
	global_load_lds_dwordx4 v2, s[46:47] offset:128
	v_mfma_f32_16x16x32_bf16 v[32:35], v[142:145], v[224:227], v[32:35]
	v_mfma_f32_16x16x32_bf16 v[28:31], v[150:153], v[224:227], v[28:31]
	v_mfma_f32_16x16x32_bf16 v[16:19], v[142:145], v[232:235], v[16:19]
	v_mfma_f32_16x16x32_bf16 v[12:15], v[150:153], v[232:235], v[12:15]
	v_mfma_f32_16x16x32_bf16 v[64:67], v[146:149], v[212:215], v[64:67]
	v_mfma_f32_16x16x32_bf16 v[60:63], v[154:157], v[212:215], v[60:63]
	v_mfma_f32_16x16x32_bf16 v[48:51], v[146:149], v[220:223], v[48:51]
	s_add_i32 m0, s61, 0xffffff80
	v_mfma_f32_16x16x32_bf16 v[44:47], v[154:157], v[220:223], v[44:47]
	global_load_lds_dwordx4 v132, s[46:47] offset:128
	v_mfma_f32_16x16x32_bf16 v[32:35], v[146:149], v[228:231], v[32:35]
	v_mfma_f32_16x16x32_bf16 v[28:31], v[154:157], v[228:231], v[28:31]
	v_mfma_f32_16x16x32_bf16 v[16:19], v[146:149], v[236:239], v[16:19]
	v_mfma_f32_16x16x32_bf16 v[12:15], v[154:157], v[236:239], v[12:15]
	s_setprio 0
	s_setprio 1
	v_mfma_f32_16x16x32_bf16 v[56:59], v[158:161], v[208:211], v[56:59]
	v_mfma_f32_16x16x32_bf16 v[52:55], v[180:183], v[208:211], v[52:55]
	v_mfma_f32_16x16x32_bf16 v[40:43], v[158:161], v[216:219], v[40:43]
	v_mfma_f32_16x16x32_bf16 v[36:39], v[180:183], v[216:219], v[36:39]
	v_mfma_f32_16x16x32_bf16 v[24:27], v[158:161], v[224:227], v[24:27]
	v_mfma_f32_16x16x32_bf16 v[20:23], v[180:183], v[224:227], v[20:23]
	v_mfma_f32_16x16x32_bf16 v[8:11], v[158:161], v[232:235], v[8:11]
	v_mfma_f32_16x16x32_bf16 v[4:7], v[180:183], v[232:235], v[4:7]
	v_mfma_f32_16x16x32_bf16 v[56:59], v[174:177], v[212:215], v[56:59]
	v_mfma_f32_16x16x32_bf16 v[52:55], v[204:207], v[212:215], v[52:55]
	v_mfma_f32_16x16x32_bf16 v[40:43], v[174:177], v[220:223], v[40:43]
	v_mfma_f32_16x16x32_bf16 v[36:39], v[204:207], v[220:223], v[36:39]
	v_mfma_f32_16x16x32_bf16 v[24:27], v[174:177], v[228:231], v[24:27]
	v_mfma_f32_16x16x32_bf16 v[20:23], v[204:207], v[228:231], v[20:23]
	v_mfma_f32_16x16x32_bf16 v[8:11], v[174:177], v[236:239], v[8:11]
	v_mfma_f32_16x16x32_bf16 v[4:7], v[204:207], v[236:239], v[4:7]
	s_setprio 0
	s_barrier
	s_add_i32 s31, s31, 2
	s_add_u32 s2, s2, 0x100
	s_addc_u32 s29, s29, 0
	s_cmp_gt_u32 s31, 29
	s_mov_b64 s[40:41], s[42:43]
	s_cbranch_scc0 .LBB0_2185
	s_and_b64 vcc, exec, s[26:27]
	s_cbranch_vccz .LBB0_2188
	s_barrier
